# v151 variant: snapshot record layout [w][half][lane] + hg_prep gate loop split over both wave pairs + newest-first phase-3b item order
# baseline (speedup 1.0000x reference)
.LBB0_883:
	s_lshl_b32 s0, s14, 7
	s_ashr_i32 s33, s14, 2
	s_and_b32 s0, s0, 0x180
	s_and_b32 s1, s14, 0xfffffe00
	s_or_b32 s0, s0, s1
	s_and_b32 s1, s33, 0x7f
	s_or_b32 s0, s0, s1
	s_cmpk_lt_i32 s33, 0x200
	s_cselect_b32 s14, s0, s14
	v_cmp_gt_i32_e32 vcc, s34, v52
	v_cmp_lt_i32_e64 s[0:1], s16, v52
	s_waitcnt lgkmcnt(0)
	s_barrier
	s_cmpk_gt_i32 s33, 0x1ff
	s_cbranch_scc1 .Lhp_keep
	v_and_b32_e32 v56, 0x7f, v52
	v_lshlrev_b32_e32 v56, 1, v56
	v_sub_f32_e32 v26, v60, v53
	v_mul_f32_e32 v26, 0xbfb8aa3b, v26
	v_exp_f32_e32 v26, v26
	v_readfirstlane_b32 s24, v52
	v_add_f32_e32 v26, 1.0, v26
	v_rcp_f32_e32 v53, v26
	v_mov_b32_e32 v27, 1.0
	s_nop 0
	v_sub_f32_e32 v26, 1.0, v53
	s_cmp_lt_u32 s24, 0x80
	s_cbranch_scc0 .Lhp_sideB
	ds_read_u16 v68, v56 offset:18432
	ds_read_u16 v76, v56
	ds_read_u16 v69, v56 offset:18704
	ds_read_u16 v77, v56 offset:272
	ds_read_u16 v70, v56 offset:18976
	ds_read_u16 v78, v56 offset:544
	ds_read_u16 v71, v56 offset:19248
	ds_read_u16 v79, v56 offset:816
	ds_read_u16 v72, v56 offset:19520
	ds_read_u16 v80, v56 offset:1088
	ds_read_u16 v73, v56 offset:19792
	ds_read_u16 v81, v56 offset:1360
	ds_read_u16 v74, v56 offset:20064
	ds_read_u16 v82, v56 offset:1632
	ds_read_u16 v75, v56 offset:20336
	ds_read_u16 v83, v56 offset:1904
	s_waitcnt lgkmcnt(0)
	v_lshlrev_b32_e32 v84, 16, v68
	v_lshlrev_b32_e32 v85, 16, v69
	v_lshlrev_b32_e32 v86, 16, v70
	v_lshlrev_b32_e32 v87, 16, v71
	v_lshlrev_b32_e32 v88, 16, v72
	v_lshlrev_b32_e32 v89, 16, v73
	v_lshlrev_b32_e32 v90, 16, v74
	v_lshlrev_b32_e32 v91, 16, v75
	v_lshlrev_b32_e32 v100, 16, v76
	v_lshlrev_b32_e32 v101, 16, v77
	v_lshlrev_b32_e32 v102, 16, v78
	v_lshlrev_b32_e32 v103, 16, v79
	v_lshlrev_b32_e32 v104, 16, v80
	v_lshlrev_b32_e32 v105, 16, v81
	v_lshlrev_b32_e32 v106, 16, v82
	v_lshlrev_b32_e32 v107, 16, v83
	ds_read_u16 v116, v56 offset:20608
	ds_read_u16 v124, v56 offset:2176
	ds_read_u16 v117, v56 offset:20880
	ds_read_u16 v125, v56 offset:2448
	ds_read_u16 v118, v56 offset:21152
	ds_read_u16 v126, v56 offset:2720
	ds_read_u16 v119, v56 offset:21424
	ds_read_u16 v127, v56 offset:2992
	ds_read_u16 v120, v56 offset:21696
	ds_read_u16 v128, v56 offset:3264
	ds_read_u16 v121, v56 offset:21968
	ds_read_u16 v129, v56 offset:3536
	ds_read_u16 v122, v56 offset:22240
	ds_read_u16 v130, v56 offset:3808
	ds_read_u16 v123, v56 offset:22512
	ds_read_u16 v131, v56 offset:4080
	v_mul_f32_e32 v84, 0xbfb8aa3b, v84
	v_mul_f32_e32 v85, 0xbfb8aa3b, v85
	v_mul_f32_e32 v86, 0xbfb8aa3b, v86
	v_mul_f32_e32 v87, 0xbfb8aa3b, v87
	v_mul_f32_e32 v88, 0xbfb8aa3b, v88
	v_mul_f32_e32 v89, 0xbfb8aa3b, v89
	v_mul_f32_e32 v90, 0xbfb8aa3b, v90
	v_mul_f32_e32 v91, 0xbfb8aa3b, v91
	v_mul_f32_e32 v108, 0xbfb8aa3b, v100
	v_mul_f32_e32 v109, 0xbfb8aa3b, v101
	v_mul_f32_e32 v110, 0xbfb8aa3b, v102
	v_mul_f32_e32 v111, 0xbfb8aa3b, v103
	v_mul_f32_e32 v112, 0xbfb8aa3b, v104
	v_mul_f32_e32 v113, 0xbfb8aa3b, v105
	v_mul_f32_e32 v114, 0xbfb8aa3b, v106
	v_mul_f32_e32 v115, 0xbfb8aa3b, v107
	v_exp_f32_e32 v84, v84
	v_exp_f32_e32 v85, v85
	v_exp_f32_e32 v86, v86
	v_exp_f32_e32 v87, v87
	v_exp_f32_e32 v88, v88
	v_exp_f32_e32 v89, v89
	v_exp_f32_e32 v90, v90
	v_exp_f32_e32 v91, v91
	v_exp_f32_e32 v108, v108
	v_exp_f32_e32 v109, v109
	v_exp_f32_e32 v110, v110
	v_exp_f32_e32 v111, v111
	v_exp_f32_e32 v112, v112
	v_exp_f32_e32 v113, v113
	v_exp_f32_e32 v114, v114
	v_exp_f32_e32 v115, v115
	v_add_f32_e32 v84, 1.0, v84
	v_add_f32_e32 v85, 1.0, v85
	v_add_f32_e32 v86, 1.0, v86
	v_add_f32_e32 v87, 1.0, v87
	v_add_f32_e32 v88, 1.0, v88
	v_add_f32_e32 v89, 1.0, v89
	v_add_f32_e32 v90, 1.0, v90
	v_add_f32_e32 v91, 1.0, v91
	v_add_f32_e32 v108, 1.0, v108
	v_add_f32_e32 v109, 1.0, v109
	v_add_f32_e32 v110, 1.0, v110
	v_add_f32_e32 v111, 1.0, v111
	v_add_f32_e32 v112, 1.0, v112
	v_add_f32_e32 v113, 1.0, v113
	v_add_f32_e32 v114, 1.0, v114
	v_add_f32_e32 v115, 1.0, v115
	v_rcp_f32_e32 v84, v84
	v_rcp_f32_e32 v85, v85
	v_rcp_f32_e32 v86, v86
	v_rcp_f32_e32 v87, v87
	v_rcp_f32_e32 v88, v88
	v_rcp_f32_e32 v89, v89
	v_rcp_f32_e32 v90, v90
	v_rcp_f32_e32 v91, v91
	v_rcp_f32_e32 v108, v108
	v_rcp_f32_e32 v109, v109
	v_rcp_f32_e32 v110, v110
	v_rcp_f32_e32 v111, v111
	v_rcp_f32_e32 v112, v112
	v_rcp_f32_e32 v113, v113
	v_rcp_f32_e32 v114, v114
	v_rcp_f32_e32 v115, v115
	v_sub_f32_e32 v92, 1.0, v84
	v_sub_f32_e32 v93, 1.0, v85
	v_sub_f32_e32 v94, 1.0, v86
	v_sub_f32_e32 v95, 1.0, v87
	v_sub_f32_e32 v96, 1.0, v88
	v_sub_f32_e32 v97, 1.0, v89
	v_sub_f32_e32 v98, 1.0, v90
	v_sub_f32_e32 v99, 1.0, v91
	v_fma_f32 v84, v26, v84, v53
	v_fma_f32 v85, v26, v85, v53
	v_fma_f32 v86, v26, v86, v53
	v_fma_f32 v87, v26, v87, v53
	v_fma_f32 v88, v26, v88, v53
	v_fma_f32 v89, v26, v89, v53
	v_fma_f32 v90, v26, v90, v53
	v_fma_f32 v91, v26, v91, v53
	v_mul_f32_e32 v92, v26, v92
	v_mul_f32_e32 v93, v26, v93
	v_mul_f32_e32 v94, v26, v94
	v_mul_f32_e32 v95, v26, v95
	v_mul_f32_e32 v96, v26, v96
	v_mul_f32_e32 v97, v26, v97
	v_mul_f32_e32 v98, v26, v98
	v_mul_f32_e32 v99, v26, v99
	v_mul_f32_e32 v108, v108, v100
	v_mul_f32_e32 v109, v109, v101
	v_mul_f32_e32 v110, v110, v102
	v_mul_f32_e32 v111, v111, v103
	v_mul_f32_e32 v112, v112, v104
	v_mul_f32_e32 v113, v113, v105
	v_mul_f32_e32 v114, v114, v106
	v_mul_f32_e32 v115, v115, v107
	v_mul_f32_e32 v84, v27, v84
	v_mul_f32_e32 v85, v84, v85
	v_mul_f32_e32 v86, v85, v86
	v_mul_f32_e32 v87, v86, v87
	v_mul_f32_e32 v88, v87, v88
	v_mul_f32_e32 v89, v88, v89
	v_mul_f32_e32 v90, v89, v90
	v_mul_f32_e32 v91, v90, v91
	v_mov_b32_e32 v27, v91
	v_rcp_f32_e32 v100, v84
	v_rcp_f32_e32 v101, v85
	v_rcp_f32_e32 v102, v86
	v_rcp_f32_e32 v103, v87
	v_rcp_f32_e32 v104, v88
	v_rcp_f32_e32 v105, v89
	v_rcp_f32_e32 v106, v90
	v_rcp_f32_e32 v107, v91
	v_mul_f32_e32 v108, v84, v108
	v_mul_f32_e32 v109, v85, v109
	v_mul_f32_e32 v110, v86, v110
	v_mul_f32_e32 v111, v87, v111
	v_mul_f32_e32 v112, v88, v112
	v_mul_f32_e32 v113, v89, v113
	v_mul_f32_e32 v114, v90, v114
	v_mul_f32_e32 v115, v91, v115
	v_mul_f32_e32 v92, v92, v100
	v_mul_f32_e32 v93, v93, v101
	v_mul_f32_e32 v94, v94, v102
	v_mul_f32_e32 v95, v95, v103
	v_mul_f32_e32 v96, v96, v104
	v_mul_f32_e32 v97, v97, v105
	v_mul_f32_e32 v98, v98, v106
	v_mul_f32_e32 v99, v99, v107
	v_cvt_pk_bf16_f32 v92, v92, v108
	v_cvt_pk_bf16_f32 v93, v93, v109
	v_cvt_pk_bf16_f32 v94, v94, v110
	v_cvt_pk_bf16_f32 v95, v95, v111
	v_cvt_pk_bf16_f32 v96, v96, v112
	v_cvt_pk_bf16_f32 v97, v97, v113
	v_cvt_pk_bf16_f32 v98, v98, v114
	v_cvt_pk_bf16_f32 v99, v99, v115
	s_waitcnt lgkmcnt(0)
	ds_write_b16_d16_hi v56, v92
	ds_write_b16 v56, v92 offset:18432
	ds_write_b16_d16_hi v56, v93 offset:272
	ds_write_b16 v56, v93 offset:18704
	ds_write_b16_d16_hi v56, v94 offset:544
	ds_write_b16 v56, v94 offset:18976
	ds_write_b16_d16_hi v56, v95 offset:816
	ds_write_b16 v56, v95 offset:19248
	ds_write_b16_d16_hi v56, v96 offset:1088
	ds_write_b16 v56, v96 offset:19520
	ds_write_b16_d16_hi v56, v97 offset:1360
	ds_write_b16 v56, v97 offset:19792
	ds_write_b16_d16_hi v56, v98 offset:1632
	ds_write_b16 v56, v98 offset:20064
	ds_write_b16_d16_hi v56, v99 offset:1904
	ds_write_b16 v56, v99 offset:20336
	v_lshlrev_b32_e32 v84, 16, v116
	v_lshlrev_b32_e32 v85, 16, v117
	v_lshlrev_b32_e32 v86, 16, v118
	v_lshlrev_b32_e32 v87, 16, v119
	v_lshlrev_b32_e32 v88, 16, v120
	v_lshlrev_b32_e32 v89, 16, v121
	v_lshlrev_b32_e32 v90, 16, v122
	v_lshlrev_b32_e32 v91, 16, v123
	v_lshlrev_b32_e32 v100, 16, v124
	v_lshlrev_b32_e32 v101, 16, v125
	v_lshlrev_b32_e32 v102, 16, v126
	v_lshlrev_b32_e32 v103, 16, v127
	v_lshlrev_b32_e32 v104, 16, v128
	v_lshlrev_b32_e32 v105, 16, v129
	v_lshlrev_b32_e32 v106, 16, v130
	v_lshlrev_b32_e32 v107, 16, v131
	ds_read_u16 v68, v56 offset:22784
	ds_read_u16 v76, v56 offset:4352
	ds_read_u16 v69, v56 offset:23056
	ds_read_u16 v77, v56 offset:4624
	ds_read_u16 v70, v56 offset:23328
	ds_read_u16 v78, v56 offset:4896
	ds_read_u16 v71, v56 offset:23600
	ds_read_u16 v79, v56 offset:5168
	ds_read_u16 v72, v56 offset:23872
	ds_read_u16 v80, v56 offset:5440
	ds_read_u16 v73, v56 offset:24144
	ds_read_u16 v81, v56 offset:5712
	ds_read_u16 v74, v56 offset:24416
	ds_read_u16 v82, v56 offset:5984
	ds_read_u16 v75, v56 offset:24688
	ds_read_u16 v83, v56 offset:6256
	v_mul_f32_e32 v84, 0xbfb8aa3b, v84
	v_mul_f32_e32 v85, 0xbfb8aa3b, v85
	v_mul_f32_e32 v86, 0xbfb8aa3b, v86
	v_mul_f32_e32 v87, 0xbfb8aa3b, v87
	v_mul_f32_e32 v88, 0xbfb8aa3b, v88
	v_mul_f32_e32 v89, 0xbfb8aa3b, v89
	v_mul_f32_e32 v90, 0xbfb8aa3b, v90
	v_mul_f32_e32 v91, 0xbfb8aa3b, v91
	v_mul_f32_e32 v108, 0xbfb8aa3b, v100
	v_mul_f32_e32 v109, 0xbfb8aa3b, v101
	v_mul_f32_e32 v110, 0xbfb8aa3b, v102
	v_mul_f32_e32 v111, 0xbfb8aa3b, v103
	v_mul_f32_e32 v112, 0xbfb8aa3b, v104
	v_mul_f32_e32 v113, 0xbfb8aa3b, v105
	v_mul_f32_e32 v114, 0xbfb8aa3b, v106
	v_mul_f32_e32 v115, 0xbfb8aa3b, v107
	v_exp_f32_e32 v84, v84
	v_exp_f32_e32 v85, v85
	v_exp_f32_e32 v86, v86
	v_exp_f32_e32 v87, v87
	v_exp_f32_e32 v88, v88
	v_exp_f32_e32 v89, v89
	v_exp_f32_e32 v90, v90
	v_exp_f32_e32 v91, v91
	v_exp_f32_e32 v108, v108
	v_exp_f32_e32 v109, v109
	v_exp_f32_e32 v110, v110
	v_exp_f32_e32 v111, v111
	v_exp_f32_e32 v112, v112
	v_exp_f32_e32 v113, v113
	v_exp_f32_e32 v114, v114
	v_exp_f32_e32 v115, v115
	v_add_f32_e32 v84, 1.0, v84
	v_add_f32_e32 v85, 1.0, v85
	v_add_f32_e32 v86, 1.0, v86
	v_add_f32_e32 v87, 1.0, v87
	v_add_f32_e32 v88, 1.0, v88
	v_add_f32_e32 v89, 1.0, v89
	v_add_f32_e32 v90, 1.0, v90
	v_add_f32_e32 v91, 1.0, v91
	v_add_f32_e32 v108, 1.0, v108
	v_add_f32_e32 v109, 1.0, v109
	v_add_f32_e32 v110, 1.0, v110
	v_add_f32_e32 v111, 1.0, v111
	v_add_f32_e32 v112, 1.0, v112
	v_add_f32_e32 v113, 1.0, v113
	v_add_f32_e32 v114, 1.0, v114
	v_add_f32_e32 v115, 1.0, v115
	v_rcp_f32_e32 v84, v84
	v_rcp_f32_e32 v85, v85
	v_rcp_f32_e32 v86, v86
	v_rcp_f32_e32 v87, v87
	v_rcp_f32_e32 v88, v88
	v_rcp_f32_e32 v89, v89
	v_rcp_f32_e32 v90, v90
	v_rcp_f32_e32 v91, v91
	v_rcp_f32_e32 v108, v108
	v_rcp_f32_e32 v109, v109
	v_rcp_f32_e32 v110, v110
	v_rcp_f32_e32 v111, v111
	v_rcp_f32_e32 v112, v112
	v_rcp_f32_e32 v113, v113
	v_rcp_f32_e32 v114, v114
	v_rcp_f32_e32 v115, v115
	v_sub_f32_e32 v92, 1.0, v84
	v_sub_f32_e32 v93, 1.0, v85
	v_sub_f32_e32 v94, 1.0, v86
	v_sub_f32_e32 v95, 1.0, v87
	v_sub_f32_e32 v96, 1.0, v88
	v_sub_f32_e32 v97, 1.0, v89
	v_sub_f32_e32 v98, 1.0, v90
	v_sub_f32_e32 v99, 1.0, v91
	v_fma_f32 v84, v26, v84, v53
	v_fma_f32 v85, v26, v85, v53
	v_fma_f32 v86, v26, v86, v53
	v_fma_f32 v87, v26, v87, v53
	v_fma_f32 v88, v26, v88, v53
	v_fma_f32 v89, v26, v89, v53
	v_fma_f32 v90, v26, v90, v53
	v_fma_f32 v91, v26, v91, v53
	v_mul_f32_e32 v92, v26, v92
	v_mul_f32_e32 v93, v26, v93
	v_mul_f32_e32 v94, v26, v94
	v_mul_f32_e32 v95, v26, v95
	v_mul_f32_e32 v96, v26, v96
	v_mul_f32_e32 v97, v26, v97
	v_mul_f32_e32 v98, v26, v98
	v_mul_f32_e32 v99, v26, v99
	v_mul_f32_e32 v108, v108, v100
	v_mul_f32_e32 v109, v109, v101
	v_mul_f32_e32 v110, v110, v102
	v_mul_f32_e32 v111, v111, v103
	v_mul_f32_e32 v112, v112, v104
	v_mul_f32_e32 v113, v113, v105
	v_mul_f32_e32 v114, v114, v106
	v_mul_f32_e32 v115, v115, v107
	v_mul_f32_e32 v84, v27, v84
	v_mul_f32_e32 v85, v84, v85
	v_mul_f32_e32 v86, v85, v86
	v_mul_f32_e32 v87, v86, v87
	v_mul_f32_e32 v88, v87, v88
	v_mul_f32_e32 v89, v88, v89
	v_mul_f32_e32 v90, v89, v90
	v_mul_f32_e32 v91, v90, v91
	v_mov_b32_e32 v27, v91
	v_rcp_f32_e32 v100, v84
	v_rcp_f32_e32 v101, v85
	v_rcp_f32_e32 v102, v86
	v_rcp_f32_e32 v103, v87
	v_rcp_f32_e32 v104, v88
	v_rcp_f32_e32 v105, v89
	v_rcp_f32_e32 v106, v90
	v_rcp_f32_e32 v107, v91
	v_mul_f32_e32 v108, v84, v108
	v_mul_f32_e32 v109, v85, v109
	v_mul_f32_e32 v110, v86, v110
	v_mul_f32_e32 v111, v87, v111
	v_mul_f32_e32 v112, v88, v112
	v_mul_f32_e32 v113, v89, v113
	v_mul_f32_e32 v114, v90, v114
	v_mul_f32_e32 v115, v91, v115
	v_mul_f32_e32 v92, v92, v100
	v_mul_f32_e32 v93, v93, v101
	v_mul_f32_e32 v94, v94, v102
	v_mul_f32_e32 v95, v95, v103
	v_mul_f32_e32 v96, v96, v104
	v_mul_f32_e32 v97, v97, v105
	v_mul_f32_e32 v98, v98, v106
	v_mul_f32_e32 v99, v99, v107
	v_cvt_pk_bf16_f32 v92, v92, v108
	v_cvt_pk_bf16_f32 v93, v93, v109
	v_cvt_pk_bf16_f32 v94, v94, v110
	v_cvt_pk_bf16_f32 v95, v95, v111
	v_cvt_pk_bf16_f32 v96, v96, v112
	v_cvt_pk_bf16_f32 v97, v97, v113
	v_cvt_pk_bf16_f32 v98, v98, v114
	v_cvt_pk_bf16_f32 v99, v99, v115
	s_waitcnt lgkmcnt(0)
	ds_write_b16_d16_hi v56, v92 offset:2176
	ds_write_b16 v56, v92 offset:20608
	ds_write_b16_d16_hi v56, v93 offset:2448
	ds_write_b16 v56, v93 offset:20880
	ds_write_b16_d16_hi v56, v94 offset:2720
	ds_write_b16 v56, v94 offset:21152
	ds_write_b16_d16_hi v56, v95 offset:2992
	ds_write_b16 v56, v95 offset:21424
	ds_write_b16_d16_hi v56, v96 offset:3264
	ds_write_b16 v56, v96 offset:21696
	ds_write_b16_d16_hi v56, v97 offset:3536
	ds_write_b16 v56, v97 offset:21968
	ds_write_b16_d16_hi v56, v98 offset:3808
	ds_write_b16 v56, v98 offset:22240
	ds_write_b16_d16_hi v56, v99 offset:4080
	ds_write_b16 v56, v99 offset:22512
	v_lshlrev_b32_e32 v84, 16, v68
	v_lshlrev_b32_e32 v85, 16, v69
	v_lshlrev_b32_e32 v86, 16, v70
	v_lshlrev_b32_e32 v87, 16, v71
	v_lshlrev_b32_e32 v88, 16, v72
	v_lshlrev_b32_e32 v89, 16, v73
	v_lshlrev_b32_e32 v90, 16, v74
	v_lshlrev_b32_e32 v91, 16, v75
	v_lshlrev_b32_e32 v100, 16, v76
	v_lshlrev_b32_e32 v101, 16, v77
	v_lshlrev_b32_e32 v102, 16, v78
	v_lshlrev_b32_e32 v103, 16, v79
	v_lshlrev_b32_e32 v104, 16, v80
	v_lshlrev_b32_e32 v105, 16, v81
	v_lshlrev_b32_e32 v106, 16, v82
	v_lshlrev_b32_e32 v107, 16, v83
	ds_read_u16 v116, v56 offset:24960
	ds_read_u16 v124, v56 offset:6528
	ds_read_u16 v117, v56 offset:25232
	ds_read_u16 v125, v56 offset:6800
	ds_read_u16 v118, v56 offset:25504
	ds_read_u16 v126, v56 offset:7072
	ds_read_u16 v119, v56 offset:25776
	ds_read_u16 v127, v56 offset:7344
	ds_read_u16 v120, v56 offset:26048
	ds_read_u16 v128, v56 offset:7616
	ds_read_u16 v121, v56 offset:26320
	ds_read_u16 v129, v56 offset:7888
	ds_read_u16 v122, v56 offset:26592
	ds_read_u16 v130, v56 offset:8160
	ds_read_u16 v123, v56 offset:26864
	ds_read_u16 v131, v56 offset:8432
	v_mul_f32_e32 v84, 0xbfb8aa3b, v84
	v_mul_f32_e32 v85, 0xbfb8aa3b, v85
	v_mul_f32_e32 v86, 0xbfb8aa3b, v86
	v_mul_f32_e32 v87, 0xbfb8aa3b, v87
	v_mul_f32_e32 v88, 0xbfb8aa3b, v88
	v_mul_f32_e32 v89, 0xbfb8aa3b, v89
	v_mul_f32_e32 v90, 0xbfb8aa3b, v90
	v_mul_f32_e32 v91, 0xbfb8aa3b, v91
	v_mul_f32_e32 v108, 0xbfb8aa3b, v100
	v_mul_f32_e32 v109, 0xbfb8aa3b, v101
	v_mul_f32_e32 v110, 0xbfb8aa3b, v102
	v_mul_f32_e32 v111, 0xbfb8aa3b, v103
	v_mul_f32_e32 v112, 0xbfb8aa3b, v104
	v_mul_f32_e32 v113, 0xbfb8aa3b, v105
	v_mul_f32_e32 v114, 0xbfb8aa3b, v106
	v_mul_f32_e32 v115, 0xbfb8aa3b, v107
	v_exp_f32_e32 v84, v84
	v_exp_f32_e32 v85, v85
	v_exp_f32_e32 v86, v86
	v_exp_f32_e32 v87, v87
	v_exp_f32_e32 v88, v88
	v_exp_f32_e32 v89, v89
	v_exp_f32_e32 v90, v90
	v_exp_f32_e32 v91, v91
	v_exp_f32_e32 v108, v108
	v_exp_f32_e32 v109, v109
	v_exp_f32_e32 v110, v110
	v_exp_f32_e32 v111, v111
	v_exp_f32_e32 v112, v112
	v_exp_f32_e32 v113, v113
	v_exp_f32_e32 v114, v114
	v_exp_f32_e32 v115, v115
	v_add_f32_e32 v84, 1.0, v84
	v_add_f32_e32 v85, 1.0, v85
	v_add_f32_e32 v86, 1.0, v86
	v_add_f32_e32 v87, 1.0, v87
	v_add_f32_e32 v88, 1.0, v88
	v_add_f32_e32 v89, 1.0, v89
	v_add_f32_e32 v90, 1.0, v90
	v_add_f32_e32 v91, 1.0, v91
	v_add_f32_e32 v108, 1.0, v108
	v_add_f32_e32 v109, 1.0, v109
	v_add_f32_e32 v110, 1.0, v110
	v_add_f32_e32 v111, 1.0, v111
	v_add_f32_e32 v112, 1.0, v112
	v_add_f32_e32 v113, 1.0, v113
	v_add_f32_e32 v114, 1.0, v114
	v_add_f32_e32 v115, 1.0, v115
	v_rcp_f32_e32 v84, v84
	v_rcp_f32_e32 v85, v85
	v_rcp_f32_e32 v86, v86
	v_rcp_f32_e32 v87, v87
	v_rcp_f32_e32 v88, v88
	v_rcp_f32_e32 v89, v89
	v_rcp_f32_e32 v90, v90
	v_rcp_f32_e32 v91, v91
	v_rcp_f32_e32 v108, v108
	v_rcp_f32_e32 v109, v109
	v_rcp_f32_e32 v110, v110
	v_rcp_f32_e32 v111, v111
	v_rcp_f32_e32 v112, v112
	v_rcp_f32_e32 v113, v113
	v_rcp_f32_e32 v114, v114
	v_rcp_f32_e32 v115, v115
	v_sub_f32_e32 v92, 1.0, v84
	v_sub_f32_e32 v93, 1.0, v85
	v_sub_f32_e32 v94, 1.0, v86
	v_sub_f32_e32 v95, 1.0, v87
	v_sub_f32_e32 v96, 1.0, v88
	v_sub_f32_e32 v97, 1.0, v89
	v_sub_f32_e32 v98, 1.0, v90
	v_sub_f32_e32 v99, 1.0, v91
	v_fma_f32 v84, v26, v84, v53
	v_fma_f32 v85, v26, v85, v53
	v_fma_f32 v86, v26, v86, v53
	v_fma_f32 v87, v26, v87, v53
	v_fma_f32 v88, v26, v88, v53
	v_fma_f32 v89, v26, v89, v53
	v_fma_f32 v90, v26, v90, v53
	v_fma_f32 v91, v26, v91, v53
	v_mul_f32_e32 v92, v26, v92
	v_mul_f32_e32 v93, v26, v93
	v_mul_f32_e32 v94, v26, v94
	v_mul_f32_e32 v95, v26, v95
	v_mul_f32_e32 v96, v26, v96
	v_mul_f32_e32 v97, v26, v97
	v_mul_f32_e32 v98, v26, v98
	v_mul_f32_e32 v99, v26, v99
	v_mul_f32_e32 v108, v108, v100
	v_mul_f32_e32 v109, v109, v101
	v_mul_f32_e32 v110, v110, v102
	v_mul_f32_e32 v111, v111, v103
	v_mul_f32_e32 v112, v112, v104
	v_mul_f32_e32 v113, v113, v105
	v_mul_f32_e32 v114, v114, v106
	v_mul_f32_e32 v115, v115, v107
	v_mul_f32_e32 v84, v27, v84
	v_mul_f32_e32 v85, v84, v85
	v_mul_f32_e32 v86, v85, v86
	v_mul_f32_e32 v87, v86, v87
	v_mul_f32_e32 v88, v87, v88
	v_mul_f32_e32 v89, v88, v89
	v_mul_f32_e32 v90, v89, v90
	v_mul_f32_e32 v91, v90, v91
	v_mov_b32_e32 v27, v91
	v_rcp_f32_e32 v100, v84
	v_rcp_f32_e32 v101, v85
	v_rcp_f32_e32 v102, v86
	v_rcp_f32_e32 v103, v87
	v_rcp_f32_e32 v104, v88
	v_rcp_f32_e32 v105, v89
	v_rcp_f32_e32 v106, v90
	v_rcp_f32_e32 v107, v91
	v_mul_f32_e32 v108, v84, v108
	v_mul_f32_e32 v109, v85, v109
	v_mul_f32_e32 v110, v86, v110
	v_mul_f32_e32 v111, v87, v111
	v_mul_f32_e32 v112, v88, v112
	v_mul_f32_e32 v113, v89, v113
	v_mul_f32_e32 v114, v90, v114
	v_mul_f32_e32 v115, v91, v115
	v_mul_f32_e32 v92, v92, v100
	v_mul_f32_e32 v93, v93, v101
	v_mul_f32_e32 v94, v94, v102
	v_mul_f32_e32 v95, v95, v103
	v_mul_f32_e32 v96, v96, v104
	v_mul_f32_e32 v97, v97, v105
	v_mul_f32_e32 v98, v98, v106
	v_mul_f32_e32 v99, v99, v107
	v_cvt_pk_bf16_f32 v92, v92, v108
	v_cvt_pk_bf16_f32 v93, v93, v109
	v_cvt_pk_bf16_f32 v94, v94, v110
	v_cvt_pk_bf16_f32 v95, v95, v111
	v_cvt_pk_bf16_f32 v96, v96, v112
	v_cvt_pk_bf16_f32 v97, v97, v113
	v_cvt_pk_bf16_f32 v98, v98, v114
	v_cvt_pk_bf16_f32 v99, v99, v115
	s_waitcnt lgkmcnt(0)
	ds_write_b16_d16_hi v56, v92 offset:4352
	ds_write_b16 v56, v92 offset:22784
	ds_write_b16_d16_hi v56, v93 offset:4624
	ds_write_b16 v56, v93 offset:23056
	ds_write_b16_d16_hi v56, v94 offset:4896
	ds_write_b16 v56, v94 offset:23328
	ds_write_b16_d16_hi v56, v95 offset:5168
	ds_write_b16 v56, v95 offset:23600
	ds_write_b16_d16_hi v56, v96 offset:5440
	ds_write_b16 v56, v96 offset:23872
	ds_write_b16_d16_hi v56, v97 offset:5712
	ds_write_b16 v56, v97 offset:24144
	ds_write_b16_d16_hi v56, v98 offset:5984
	ds_write_b16 v56, v98 offset:24416
	ds_write_b16_d16_hi v56, v99 offset:6256
	ds_write_b16 v56, v99 offset:24688
	v_lshlrev_b32_e32 v84, 16, v116
	v_lshlrev_b32_e32 v85, 16, v117
	v_lshlrev_b32_e32 v86, 16, v118
	v_lshlrev_b32_e32 v87, 16, v119
	v_lshlrev_b32_e32 v88, 16, v120
	v_lshlrev_b32_e32 v89, 16, v121
	v_lshlrev_b32_e32 v90, 16, v122
	v_lshlrev_b32_e32 v91, 16, v123
	v_lshlrev_b32_e32 v100, 16, v124
	v_lshlrev_b32_e32 v101, 16, v125
	v_lshlrev_b32_e32 v102, 16, v126
	v_lshlrev_b32_e32 v103, 16, v127
	v_lshlrev_b32_e32 v104, 16, v128
	v_lshlrev_b32_e32 v105, 16, v129
	v_lshlrev_b32_e32 v106, 16, v130
	v_lshlrev_b32_e32 v107, 16, v131
	v_mul_f32_e32 v84, 0xbfb8aa3b, v84
	v_mul_f32_e32 v85, 0xbfb8aa3b, v85
	v_mul_f32_e32 v86, 0xbfb8aa3b, v86
	v_mul_f32_e32 v87, 0xbfb8aa3b, v87
	v_mul_f32_e32 v88, 0xbfb8aa3b, v88
	v_mul_f32_e32 v89, 0xbfb8aa3b, v89
	v_mul_f32_e32 v90, 0xbfb8aa3b, v90
	v_mul_f32_e32 v91, 0xbfb8aa3b, v91
	v_mul_f32_e32 v108, 0xbfb8aa3b, v100
	v_mul_f32_e32 v109, 0xbfb8aa3b, v101
	v_mul_f32_e32 v110, 0xbfb8aa3b, v102
	v_mul_f32_e32 v111, 0xbfb8aa3b, v103
	v_mul_f32_e32 v112, 0xbfb8aa3b, v104
	v_mul_f32_e32 v113, 0xbfb8aa3b, v105
	v_mul_f32_e32 v114, 0xbfb8aa3b, v106
	v_mul_f32_e32 v115, 0xbfb8aa3b, v107
	v_exp_f32_e32 v84, v84
	v_exp_f32_e32 v85, v85
	v_exp_f32_e32 v86, v86
	v_exp_f32_e32 v87, v87
	v_exp_f32_e32 v88, v88
	v_exp_f32_e32 v89, v89
	v_exp_f32_e32 v90, v90
	v_exp_f32_e32 v91, v91
	v_exp_f32_e32 v108, v108
	v_exp_f32_e32 v109, v109
	v_exp_f32_e32 v110, v110
	v_exp_f32_e32 v111, v111
	v_exp_f32_e32 v112, v112
	v_exp_f32_e32 v113, v113
	v_exp_f32_e32 v114, v114
	v_exp_f32_e32 v115, v115
	v_add_f32_e32 v84, 1.0, v84
	v_add_f32_e32 v85, 1.0, v85
	v_add_f32_e32 v86, 1.0, v86
	v_add_f32_e32 v87, 1.0, v87
	v_add_f32_e32 v88, 1.0, v88
	v_add_f32_e32 v89, 1.0, v89
	v_add_f32_e32 v90, 1.0, v90
	v_add_f32_e32 v91, 1.0, v91
	v_add_f32_e32 v108, 1.0, v108
	v_add_f32_e32 v109, 1.0, v109
	v_add_f32_e32 v110, 1.0, v110
	v_add_f32_e32 v111, 1.0, v111
	v_add_f32_e32 v112, 1.0, v112
	v_add_f32_e32 v113, 1.0, v113
	v_add_f32_e32 v114, 1.0, v114
	v_add_f32_e32 v115, 1.0, v115
	v_rcp_f32_e32 v84, v84
	v_rcp_f32_e32 v85, v85
	v_rcp_f32_e32 v86, v86
	v_rcp_f32_e32 v87, v87
	v_rcp_f32_e32 v88, v88
	v_rcp_f32_e32 v89, v89
	v_rcp_f32_e32 v90, v90
	v_rcp_f32_e32 v91, v91
	v_rcp_f32_e32 v108, v108
	v_rcp_f32_e32 v109, v109
	v_rcp_f32_e32 v110, v110
	v_rcp_f32_e32 v111, v111
	v_rcp_f32_e32 v112, v112
	v_rcp_f32_e32 v113, v113
	v_rcp_f32_e32 v114, v114
	v_rcp_f32_e32 v115, v115
	v_sub_f32_e32 v92, 1.0, v84
	v_sub_f32_e32 v93, 1.0, v85
	v_sub_f32_e32 v94, 1.0, v86
	v_sub_f32_e32 v95, 1.0, v87
	v_sub_f32_e32 v96, 1.0, v88
	v_sub_f32_e32 v97, 1.0, v89
	v_sub_f32_e32 v98, 1.0, v90
	v_sub_f32_e32 v99, 1.0, v91
	v_fma_f32 v84, v26, v84, v53
	v_fma_f32 v85, v26, v85, v53
	v_fma_f32 v86, v26, v86, v53
	v_fma_f32 v87, v26, v87, v53
	v_fma_f32 v88, v26, v88, v53
	v_fma_f32 v89, v26, v89, v53
	v_fma_f32 v90, v26, v90, v53
	v_fma_f32 v91, v26, v91, v53
	v_mul_f32_e32 v92, v26, v92
	v_mul_f32_e32 v93, v26, v93
	v_mul_f32_e32 v94, v26, v94
	v_mul_f32_e32 v95, v26, v95
	v_mul_f32_e32 v96, v26, v96
	v_mul_f32_e32 v97, v26, v97
	v_mul_f32_e32 v98, v26, v98
	v_mul_f32_e32 v99, v26, v99
	v_mul_f32_e32 v108, v108, v100
	v_mul_f32_e32 v109, v109, v101
	v_mul_f32_e32 v110, v110, v102
	v_mul_f32_e32 v111, v111, v103
	v_mul_f32_e32 v112, v112, v104
	v_mul_f32_e32 v113, v113, v105
	v_mul_f32_e32 v114, v114, v106
	v_mul_f32_e32 v115, v115, v107
	v_mul_f32_e32 v84, v27, v84
	v_mul_f32_e32 v85, v84, v85
	v_mul_f32_e32 v86, v85, v86
	v_mul_f32_e32 v87, v86, v87
	v_mul_f32_e32 v88, v87, v88
	v_mul_f32_e32 v89, v88, v89
	v_mul_f32_e32 v90, v89, v90
	v_mul_f32_e32 v91, v90, v91
	v_mov_b32_e32 v27, v91
	v_rcp_f32_e32 v100, v84
	v_rcp_f32_e32 v101, v85
	v_rcp_f32_e32 v102, v86
	v_rcp_f32_e32 v103, v87
	v_rcp_f32_e32 v104, v88
	v_rcp_f32_e32 v105, v89
	v_rcp_f32_e32 v106, v90
	v_rcp_f32_e32 v107, v91
	v_mul_f32_e32 v108, v84, v108
	v_mul_f32_e32 v109, v85, v109
	v_mul_f32_e32 v110, v86, v110
	v_mul_f32_e32 v111, v87, v111
	v_mul_f32_e32 v112, v88, v112
	v_mul_f32_e32 v113, v89, v113
	v_mul_f32_e32 v114, v90, v114
	v_mul_f32_e32 v115, v91, v115
	v_mul_f32_e32 v92, v92, v100
	v_mul_f32_e32 v93, v93, v101
	v_mul_f32_e32 v94, v94, v102
	v_mul_f32_e32 v95, v95, v103
	v_mul_f32_e32 v96, v96, v104
	v_mul_f32_e32 v97, v97, v105
	v_mul_f32_e32 v98, v98, v106
	v_mul_f32_e32 v99, v99, v107
	v_cvt_pk_bf16_f32 v92, v92, v108
	v_cvt_pk_bf16_f32 v93, v93, v109
	v_cvt_pk_bf16_f32 v94, v94, v110
	v_cvt_pk_bf16_f32 v95, v95, v111
	v_cvt_pk_bf16_f32 v96, v96, v112
	v_cvt_pk_bf16_f32 v97, v97, v113
	v_cvt_pk_bf16_f32 v98, v98, v114
	v_cvt_pk_bf16_f32 v99, v99, v115
	s_waitcnt lgkmcnt(0)
	ds_write_b16_d16_hi v56, v92 offset:6528
	ds_write_b16 v56, v92 offset:24960
	ds_write_b16_d16_hi v56, v93 offset:6800
	ds_write_b16 v56, v93 offset:25232
	ds_write_b16_d16_hi v56, v94 offset:7072
	ds_write_b16 v56, v94 offset:25504
	ds_write_b16_d16_hi v56, v95 offset:7344
	ds_write_b16 v56, v95 offset:25776
	ds_write_b16_d16_hi v56, v96 offset:7616
	ds_write_b16 v56, v96 offset:26048
	ds_write_b16_d16_hi v56, v97 offset:7888
	ds_write_b16 v56, v97 offset:26320
	ds_write_b16_d16_hi v56, v98 offset:8160
	ds_write_b16 v56, v98 offset:26592
	ds_write_b16_d16_hi v56, v99 offset:8432
	ds_write_b16 v56, v99 offset:26864
	v_lshlrev_b32_e32 v84, 1, v56
	v_add_u32_e32 v84, 0x10000, v84
	ds_write_b32 v84, v27 offset:0
	s_waitcnt lgkmcnt(0)
	s_barrier
	s_barrier
	ds_read_b32 v27, v84 offset:512
	s_waitcnt lgkmcnt(0)
	s_branch .Lhp_join
.Lhp_sideB:
	ds_read_u16 v68, v56 offset:27136
	ds_read_u16 v76, v56 offset:8704
	ds_read_u16 v69, v56 offset:27408
	ds_read_u16 v77, v56 offset:8976
	ds_read_u16 v70, v56 offset:27680
	ds_read_u16 v78, v56 offset:9248
	ds_read_u16 v71, v56 offset:27952
	ds_read_u16 v79, v56 offset:9520
	ds_read_u16 v72, v56 offset:28224
	ds_read_u16 v80, v56 offset:9792
	ds_read_u16 v73, v56 offset:28496
	ds_read_u16 v81, v56 offset:10064
	ds_read_u16 v74, v56 offset:28768
	ds_read_u16 v82, v56 offset:10336
	ds_read_u16 v75, v56 offset:29040
	ds_read_u16 v83, v56 offset:10608
	s_waitcnt lgkmcnt(0)
	v_lshlrev_b32_e32 v84, 16, v68
	v_lshlrev_b32_e32 v85, 16, v69
	v_lshlrev_b32_e32 v86, 16, v70
	v_lshlrev_b32_e32 v87, 16, v71
	v_lshlrev_b32_e32 v88, 16, v72
	v_lshlrev_b32_e32 v89, 16, v73
	v_lshlrev_b32_e32 v90, 16, v74
	v_lshlrev_b32_e32 v91, 16, v75
	v_lshlrev_b32_e32 v100, 16, v76
	v_lshlrev_b32_e32 v101, 16, v77
	v_lshlrev_b32_e32 v102, 16, v78
	v_lshlrev_b32_e32 v103, 16, v79
	v_lshlrev_b32_e32 v104, 16, v80
	v_lshlrev_b32_e32 v105, 16, v81
	v_lshlrev_b32_e32 v106, 16, v82
	v_lshlrev_b32_e32 v107, 16, v83
	v_mul_f32_e32 v84, 0xbfb8aa3b, v84
	v_mul_f32_e32 v85, 0xbfb8aa3b, v85
	v_mul_f32_e32 v86, 0xbfb8aa3b, v86
	v_mul_f32_e32 v87, 0xbfb8aa3b, v87
	v_mul_f32_e32 v88, 0xbfb8aa3b, v88
	v_mul_f32_e32 v89, 0xbfb8aa3b, v89
	v_mul_f32_e32 v90, 0xbfb8aa3b, v90
	v_mul_f32_e32 v91, 0xbfb8aa3b, v91
	v_mul_f32_e32 v108, 0xbfb8aa3b, v100
	v_mul_f32_e32 v109, 0xbfb8aa3b, v101
	v_mul_f32_e32 v110, 0xbfb8aa3b, v102
	v_mul_f32_e32 v111, 0xbfb8aa3b, v103
	v_mul_f32_e32 v112, 0xbfb8aa3b, v104
	v_mul_f32_e32 v113, 0xbfb8aa3b, v105
	v_mul_f32_e32 v114, 0xbfb8aa3b, v106
	v_mul_f32_e32 v115, 0xbfb8aa3b, v107
	v_exp_f32_e32 v84, v84
	v_exp_f32_e32 v85, v85
	v_exp_f32_e32 v86, v86
	v_exp_f32_e32 v87, v87
	v_exp_f32_e32 v88, v88
	v_exp_f32_e32 v89, v89
	v_exp_f32_e32 v90, v90
	v_exp_f32_e32 v91, v91
	v_exp_f32_e32 v108, v108
	v_exp_f32_e32 v109, v109
	v_exp_f32_e32 v110, v110
	v_exp_f32_e32 v111, v111
	v_exp_f32_e32 v112, v112
	v_exp_f32_e32 v113, v113
	v_exp_f32_e32 v114, v114
	v_exp_f32_e32 v115, v115
	v_add_f32_e32 v84, 1.0, v84
	v_add_f32_e32 v85, 1.0, v85
	v_add_f32_e32 v86, 1.0, v86
	v_add_f32_e32 v87, 1.0, v87
	v_add_f32_e32 v88, 1.0, v88
	v_add_f32_e32 v89, 1.0, v89
	v_add_f32_e32 v90, 1.0, v90
	v_add_f32_e32 v91, 1.0, v91
	v_add_f32_e32 v108, 1.0, v108
	v_add_f32_e32 v109, 1.0, v109
	v_add_f32_e32 v110, 1.0, v110
	v_add_f32_e32 v111, 1.0, v111
	v_add_f32_e32 v112, 1.0, v112
	v_add_f32_e32 v113, 1.0, v113
	v_add_f32_e32 v114, 1.0, v114
	v_add_f32_e32 v115, 1.0, v115
	v_rcp_f32_e32 v84, v84
	v_rcp_f32_e32 v85, v85
	v_rcp_f32_e32 v86, v86
	v_rcp_f32_e32 v87, v87
	v_rcp_f32_e32 v88, v88
	v_rcp_f32_e32 v89, v89
	v_rcp_f32_e32 v90, v90
	v_rcp_f32_e32 v91, v91
	v_rcp_f32_e32 v108, v108
	v_rcp_f32_e32 v109, v109
	v_rcp_f32_e32 v110, v110
	v_rcp_f32_e32 v111, v111
	v_rcp_f32_e32 v112, v112
	v_rcp_f32_e32 v113, v113
	v_rcp_f32_e32 v114, v114
	v_rcp_f32_e32 v115, v115
	v_sub_f32_e32 v92, 1.0, v84
	v_sub_f32_e32 v93, 1.0, v85
	v_sub_f32_e32 v94, 1.0, v86
	v_sub_f32_e32 v95, 1.0, v87
	v_sub_f32_e32 v96, 1.0, v88
	v_sub_f32_e32 v97, 1.0, v89
	v_sub_f32_e32 v98, 1.0, v90
	v_sub_f32_e32 v99, 1.0, v91
	v_fma_f32 v84, v26, v84, v53
	v_fma_f32 v85, v26, v85, v53
	v_fma_f32 v86, v26, v86, v53
	v_fma_f32 v87, v26, v87, v53
	v_fma_f32 v88, v26, v88, v53
	v_fma_f32 v89, v26, v89, v53
	v_fma_f32 v90, v26, v90, v53
	v_fma_f32 v91, v26, v91, v53
	v_mul_f32_e32 v92, v26, v92
	v_mul_f32_e32 v93, v26, v93
	v_mul_f32_e32 v94, v26, v94
	v_mul_f32_e32 v95, v26, v95
	v_mul_f32_e32 v96, v26, v96
	v_mul_f32_e32 v97, v26, v97
	v_mul_f32_e32 v98, v26, v98
	v_mul_f32_e32 v99, v26, v99
	v_mul_f32_e32 v108, v108, v100
	v_mul_f32_e32 v109, v109, v101
	v_mul_f32_e32 v110, v110, v102
	v_mul_f32_e32 v111, v111, v103
	v_mul_f32_e32 v112, v112, v104
	v_mul_f32_e32 v113, v113, v105
	v_mul_f32_e32 v114, v114, v106
	v_mul_f32_e32 v115, v115, v107
	v_mul_f32_e32 v84, v27, v84
	v_mul_f32_e32 v85, v84, v85
	v_mul_f32_e32 v86, v85, v86
	v_mul_f32_e32 v87, v86, v87
	v_mul_f32_e32 v88, v87, v88
	v_mul_f32_e32 v89, v88, v89
	v_mul_f32_e32 v90, v89, v90
	v_mul_f32_e32 v91, v90, v91
	v_mov_b32_e32 v27, v91
	v_rcp_f32_e32 v100, v84
	v_rcp_f32_e32 v101, v85
	v_rcp_f32_e32 v102, v86
	v_rcp_f32_e32 v103, v87
	v_rcp_f32_e32 v104, v88
	v_rcp_f32_e32 v105, v89
	v_rcp_f32_e32 v106, v90
	v_rcp_f32_e32 v107, v91
	v_mul_f32_e32 v148, v84, v108
	v_mul_f32_e32 v149, v85, v109
	v_mul_f32_e32 v150, v86, v110
	v_mul_f32_e32 v151, v87, v111
	v_mul_f32_e32 v152, v88, v112
	v_mul_f32_e32 v153, v89, v113
	v_mul_f32_e32 v154, v90, v114
	v_mul_f32_e32 v155, v91, v115
	v_mul_f32_e32 v116, v92, v100
	v_mul_f32_e32 v117, v93, v101
	v_mul_f32_e32 v118, v94, v102
	v_mul_f32_e32 v119, v95, v103
	v_mul_f32_e32 v120, v96, v104
	v_mul_f32_e32 v121, v97, v105
	v_mul_f32_e32 v122, v98, v106
	v_mul_f32_e32 v123, v99, v107
	ds_read_u16 v68, v56 offset:29312
	ds_read_u16 v76, v56 offset:10880
	ds_read_u16 v69, v56 offset:29584
	ds_read_u16 v77, v56 offset:11152
	ds_read_u16 v70, v56 offset:29856
	ds_read_u16 v78, v56 offset:11424
	ds_read_u16 v71, v56 offset:30128
	ds_read_u16 v79, v56 offset:11696
	ds_read_u16 v72, v56 offset:30400
	ds_read_u16 v80, v56 offset:11968
	ds_read_u16 v73, v56 offset:30672
	ds_read_u16 v81, v56 offset:12240
	ds_read_u16 v74, v56 offset:30944
	ds_read_u16 v82, v56 offset:12512
	ds_read_u16 v75, v56 offset:31216
	ds_read_u16 v83, v56 offset:12784
	s_waitcnt lgkmcnt(0)
	v_lshlrev_b32_e32 v84, 16, v68
	v_lshlrev_b32_e32 v85, 16, v69
	v_lshlrev_b32_e32 v86, 16, v70
	v_lshlrev_b32_e32 v87, 16, v71
	v_lshlrev_b32_e32 v88, 16, v72
	v_lshlrev_b32_e32 v89, 16, v73
	v_lshlrev_b32_e32 v90, 16, v74
	v_lshlrev_b32_e32 v91, 16, v75
	v_lshlrev_b32_e32 v100, 16, v76
	v_lshlrev_b32_e32 v101, 16, v77
	v_lshlrev_b32_e32 v102, 16, v78
	v_lshlrev_b32_e32 v103, 16, v79
	v_lshlrev_b32_e32 v104, 16, v80
	v_lshlrev_b32_e32 v105, 16, v81
	v_lshlrev_b32_e32 v106, 16, v82
	v_lshlrev_b32_e32 v107, 16, v83
	v_mul_f32_e32 v84, 0xbfb8aa3b, v84
	v_mul_f32_e32 v85, 0xbfb8aa3b, v85
	v_mul_f32_e32 v86, 0xbfb8aa3b, v86
	v_mul_f32_e32 v87, 0xbfb8aa3b, v87
	v_mul_f32_e32 v88, 0xbfb8aa3b, v88
	v_mul_f32_e32 v89, 0xbfb8aa3b, v89
	v_mul_f32_e32 v90, 0xbfb8aa3b, v90
	v_mul_f32_e32 v91, 0xbfb8aa3b, v91
	v_mul_f32_e32 v108, 0xbfb8aa3b, v100
	v_mul_f32_e32 v109, 0xbfb8aa3b, v101
	v_mul_f32_e32 v110, 0xbfb8aa3b, v102
	v_mul_f32_e32 v111, 0xbfb8aa3b, v103
	v_mul_f32_e32 v112, 0xbfb8aa3b, v104
	v_mul_f32_e32 v113, 0xbfb8aa3b, v105
	v_mul_f32_e32 v114, 0xbfb8aa3b, v106
	v_mul_f32_e32 v115, 0xbfb8aa3b, v107
	v_exp_f32_e32 v84, v84
	v_exp_f32_e32 v85, v85
	v_exp_f32_e32 v86, v86
	v_exp_f32_e32 v87, v87
	v_exp_f32_e32 v88, v88
	v_exp_f32_e32 v89, v89
	v_exp_f32_e32 v90, v90
	v_exp_f32_e32 v91, v91
	v_exp_f32_e32 v108, v108
	v_exp_f32_e32 v109, v109
	v_exp_f32_e32 v110, v110
	v_exp_f32_e32 v111, v111
	v_exp_f32_e32 v112, v112
	v_exp_f32_e32 v113, v113
	v_exp_f32_e32 v114, v114
	v_exp_f32_e32 v115, v115
	v_add_f32_e32 v84, 1.0, v84
	v_add_f32_e32 v85, 1.0, v85
	v_add_f32_e32 v86, 1.0, v86
	v_add_f32_e32 v87, 1.0, v87
	v_add_f32_e32 v88, 1.0, v88
	v_add_f32_e32 v89, 1.0, v89
	v_add_f32_e32 v90, 1.0, v90
	v_add_f32_e32 v91, 1.0, v91
	v_add_f32_e32 v108, 1.0, v108
	v_add_f32_e32 v109, 1.0, v109
	v_add_f32_e32 v110, 1.0, v110
	v_add_f32_e32 v111, 1.0, v111
	v_add_f32_e32 v112, 1.0, v112
	v_add_f32_e32 v113, 1.0, v113
	v_add_f32_e32 v114, 1.0, v114
	v_add_f32_e32 v115, 1.0, v115
	v_rcp_f32_e32 v84, v84
	v_rcp_f32_e32 v85, v85
	v_rcp_f32_e32 v86, v86
	v_rcp_f32_e32 v87, v87
	v_rcp_f32_e32 v88, v88
	v_rcp_f32_e32 v89, v89
	v_rcp_f32_e32 v90, v90
	v_rcp_f32_e32 v91, v91
	v_rcp_f32_e32 v108, v108
	v_rcp_f32_e32 v109, v109
	v_rcp_f32_e32 v110, v110
	v_rcp_f32_e32 v111, v111
	v_rcp_f32_e32 v112, v112
	v_rcp_f32_e32 v113, v113
	v_rcp_f32_e32 v114, v114
	v_rcp_f32_e32 v115, v115
	v_sub_f32_e32 v92, 1.0, v84
	v_sub_f32_e32 v93, 1.0, v85
	v_sub_f32_e32 v94, 1.0, v86
	v_sub_f32_e32 v95, 1.0, v87
	v_sub_f32_e32 v96, 1.0, v88
	v_sub_f32_e32 v97, 1.0, v89
	v_sub_f32_e32 v98, 1.0, v90
	v_sub_f32_e32 v99, 1.0, v91
	v_fma_f32 v84, v26, v84, v53
	v_fma_f32 v85, v26, v85, v53
	v_fma_f32 v86, v26, v86, v53
	v_fma_f32 v87, v26, v87, v53
	v_fma_f32 v88, v26, v88, v53
	v_fma_f32 v89, v26, v89, v53
	v_fma_f32 v90, v26, v90, v53
	v_fma_f32 v91, v26, v91, v53
	v_mul_f32_e32 v92, v26, v92
	v_mul_f32_e32 v93, v26, v93
	v_mul_f32_e32 v94, v26, v94
	v_mul_f32_e32 v95, v26, v95
	v_mul_f32_e32 v96, v26, v96
	v_mul_f32_e32 v97, v26, v97
	v_mul_f32_e32 v98, v26, v98
	v_mul_f32_e32 v99, v26, v99
	v_mul_f32_e32 v108, v108, v100
	v_mul_f32_e32 v109, v109, v101
	v_mul_f32_e32 v110, v110, v102
	v_mul_f32_e32 v111, v111, v103
	v_mul_f32_e32 v112, v112, v104
	v_mul_f32_e32 v113, v113, v105
	v_mul_f32_e32 v114, v114, v106
	v_mul_f32_e32 v115, v115, v107
	v_mul_f32_e32 v84, v27, v84
	v_mul_f32_e32 v85, v84, v85
	v_mul_f32_e32 v86, v85, v86
	v_mul_f32_e32 v87, v86, v87
	v_mul_f32_e32 v88, v87, v88
	v_mul_f32_e32 v89, v88, v89
	v_mul_f32_e32 v90, v89, v90
	v_mul_f32_e32 v91, v90, v91
	v_mov_b32_e32 v27, v91
	v_rcp_f32_e32 v100, v84
	v_rcp_f32_e32 v101, v85
	v_rcp_f32_e32 v102, v86
	v_rcp_f32_e32 v103, v87
	v_rcp_f32_e32 v104, v88
	v_rcp_f32_e32 v105, v89
	v_rcp_f32_e32 v106, v90
	v_rcp_f32_e32 v107, v91
	v_mul_f32_e32 v156, v84, v108
	v_mul_f32_e32 v157, v85, v109
	v_mul_f32_e32 v158, v86, v110
	v_mul_f32_e32 v159, v87, v111
	v_mul_f32_e32 v160, v88, v112
	v_mul_f32_e32 v161, v89, v113
	v_mul_f32_e32 v162, v90, v114
	v_mul_f32_e32 v163, v91, v115
	v_mul_f32_e32 v124, v92, v100
	v_mul_f32_e32 v125, v93, v101
	v_mul_f32_e32 v126, v94, v102
	v_mul_f32_e32 v127, v95, v103
	v_mul_f32_e32 v128, v96, v104
	v_mul_f32_e32 v129, v97, v105
	v_mul_f32_e32 v130, v98, v106
	v_mul_f32_e32 v131, v99, v107
	ds_read_u16 v68, v56 offset:31488
	ds_read_u16 v76, v56 offset:13056
	ds_read_u16 v69, v56 offset:31760
	ds_read_u16 v77, v56 offset:13328
	ds_read_u16 v70, v56 offset:32032
	ds_read_u16 v78, v56 offset:13600
	ds_read_u16 v71, v56 offset:32304
	ds_read_u16 v79, v56 offset:13872
	ds_read_u16 v72, v56 offset:32576
	ds_read_u16 v80, v56 offset:14144
	ds_read_u16 v73, v56 offset:32848
	ds_read_u16 v81, v56 offset:14416
	ds_read_u16 v74, v56 offset:33120
	ds_read_u16 v82, v56 offset:14688
	ds_read_u16 v75, v56 offset:33392
	ds_read_u16 v83, v56 offset:14960
	s_waitcnt lgkmcnt(0)
	v_lshlrev_b32_e32 v84, 16, v68
	v_lshlrev_b32_e32 v85, 16, v69
	v_lshlrev_b32_e32 v86, 16, v70
	v_lshlrev_b32_e32 v87, 16, v71
	v_lshlrev_b32_e32 v88, 16, v72
	v_lshlrev_b32_e32 v89, 16, v73
	v_lshlrev_b32_e32 v90, 16, v74
	v_lshlrev_b32_e32 v91, 16, v75
	v_lshlrev_b32_e32 v100, 16, v76
	v_lshlrev_b32_e32 v101, 16, v77
	v_lshlrev_b32_e32 v102, 16, v78
	v_lshlrev_b32_e32 v103, 16, v79
	v_lshlrev_b32_e32 v104, 16, v80
	v_lshlrev_b32_e32 v105, 16, v81
	v_lshlrev_b32_e32 v106, 16, v82
	v_lshlrev_b32_e32 v107, 16, v83
	v_mul_f32_e32 v84, 0xbfb8aa3b, v84
	v_mul_f32_e32 v85, 0xbfb8aa3b, v85
	v_mul_f32_e32 v86, 0xbfb8aa3b, v86
	v_mul_f32_e32 v87, 0xbfb8aa3b, v87
	v_mul_f32_e32 v88, 0xbfb8aa3b, v88
	v_mul_f32_e32 v89, 0xbfb8aa3b, v89
	v_mul_f32_e32 v90, 0xbfb8aa3b, v90
	v_mul_f32_e32 v91, 0xbfb8aa3b, v91
	v_mul_f32_e32 v108, 0xbfb8aa3b, v100
	v_mul_f32_e32 v109, 0xbfb8aa3b, v101
	v_mul_f32_e32 v110, 0xbfb8aa3b, v102
	v_mul_f32_e32 v111, 0xbfb8aa3b, v103
	v_mul_f32_e32 v112, 0xbfb8aa3b, v104
	v_mul_f32_e32 v113, 0xbfb8aa3b, v105
	v_mul_f32_e32 v114, 0xbfb8aa3b, v106
	v_mul_f32_e32 v115, 0xbfb8aa3b, v107
	v_exp_f32_e32 v84, v84
	v_exp_f32_e32 v85, v85
	v_exp_f32_e32 v86, v86
	v_exp_f32_e32 v87, v87
	v_exp_f32_e32 v88, v88
	v_exp_f32_e32 v89, v89
	v_exp_f32_e32 v90, v90
	v_exp_f32_e32 v91, v91
	v_exp_f32_e32 v108, v108
	v_exp_f32_e32 v109, v109
	v_exp_f32_e32 v110, v110
	v_exp_f32_e32 v111, v111
	v_exp_f32_e32 v112, v112
	v_exp_f32_e32 v113, v113
	v_exp_f32_e32 v114, v114
	v_exp_f32_e32 v115, v115
	v_add_f32_e32 v84, 1.0, v84
	v_add_f32_e32 v85, 1.0, v85
	v_add_f32_e32 v86, 1.0, v86
	v_add_f32_e32 v87, 1.0, v87
	v_add_f32_e32 v88, 1.0, v88
	v_add_f32_e32 v89, 1.0, v89
	v_add_f32_e32 v90, 1.0, v90
	v_add_f32_e32 v91, 1.0, v91
	v_add_f32_e32 v108, 1.0, v108
	v_add_f32_e32 v109, 1.0, v109
	v_add_f32_e32 v110, 1.0, v110
	v_add_f32_e32 v111, 1.0, v111
	v_add_f32_e32 v112, 1.0, v112
	v_add_f32_e32 v113, 1.0, v113
	v_add_f32_e32 v114, 1.0, v114
	v_add_f32_e32 v115, 1.0, v115
	v_rcp_f32_e32 v84, v84
	v_rcp_f32_e32 v85, v85
	v_rcp_f32_e32 v86, v86
	v_rcp_f32_e32 v87, v87
	v_rcp_f32_e32 v88, v88
	v_rcp_f32_e32 v89, v89
	v_rcp_f32_e32 v90, v90
	v_rcp_f32_e32 v91, v91
	v_rcp_f32_e32 v108, v108
	v_rcp_f32_e32 v109, v109
	v_rcp_f32_e32 v110, v110
	v_rcp_f32_e32 v111, v111
	v_rcp_f32_e32 v112, v112
	v_rcp_f32_e32 v113, v113
	v_rcp_f32_e32 v114, v114
	v_rcp_f32_e32 v115, v115
	v_sub_f32_e32 v92, 1.0, v84
	v_sub_f32_e32 v93, 1.0, v85
	v_sub_f32_e32 v94, 1.0, v86
	v_sub_f32_e32 v95, 1.0, v87
	v_sub_f32_e32 v96, 1.0, v88
	v_sub_f32_e32 v97, 1.0, v89
	v_sub_f32_e32 v98, 1.0, v90
	v_sub_f32_e32 v99, 1.0, v91
	v_fma_f32 v84, v26, v84, v53
	v_fma_f32 v85, v26, v85, v53
	v_fma_f32 v86, v26, v86, v53
	v_fma_f32 v87, v26, v87, v53
	v_fma_f32 v88, v26, v88, v53
	v_fma_f32 v89, v26, v89, v53
	v_fma_f32 v90, v26, v90, v53
	v_fma_f32 v91, v26, v91, v53
	v_mul_f32_e32 v92, v26, v92
	v_mul_f32_e32 v93, v26, v93
	v_mul_f32_e32 v94, v26, v94
	v_mul_f32_e32 v95, v26, v95
	v_mul_f32_e32 v96, v26, v96
	v_mul_f32_e32 v97, v26, v97
	v_mul_f32_e32 v98, v26, v98
	v_mul_f32_e32 v99, v26, v99
	v_mul_f32_e32 v108, v108, v100
	v_mul_f32_e32 v109, v109, v101
	v_mul_f32_e32 v110, v110, v102
	v_mul_f32_e32 v111, v111, v103
	v_mul_f32_e32 v112, v112, v104
	v_mul_f32_e32 v113, v113, v105
	v_mul_f32_e32 v114, v114, v106
	v_mul_f32_e32 v115, v115, v107
	v_mul_f32_e32 v84, v27, v84
	v_mul_f32_e32 v85, v84, v85
	v_mul_f32_e32 v86, v85, v86
	v_mul_f32_e32 v87, v86, v87
	v_mul_f32_e32 v88, v87, v88
	v_mul_f32_e32 v89, v88, v89
	v_mul_f32_e32 v90, v89, v90
	v_mul_f32_e32 v91, v90, v91
	v_mov_b32_e32 v27, v91
	v_rcp_f32_e32 v100, v84
	v_rcp_f32_e32 v101, v85
	v_rcp_f32_e32 v102, v86
	v_rcp_f32_e32 v103, v87
	v_rcp_f32_e32 v104, v88
	v_rcp_f32_e32 v105, v89
	v_rcp_f32_e32 v106, v90
	v_rcp_f32_e32 v107, v91
	v_mul_f32_e32 v164, v84, v108
	v_mul_f32_e32 v165, v85, v109
	v_mul_f32_e32 v166, v86, v110
	v_mul_f32_e32 v167, v87, v111
	v_mul_f32_e32 v168, v88, v112
	v_mul_f32_e32 v169, v89, v113
	v_mul_f32_e32 v170, v90, v114
	v_mul_f32_e32 v171, v91, v115
	v_mul_f32_e32 v132, v92, v100
	v_mul_f32_e32 v133, v93, v101
	v_mul_f32_e32 v134, v94, v102
	v_mul_f32_e32 v135, v95, v103
	v_mul_f32_e32 v136, v96, v104
	v_mul_f32_e32 v137, v97, v105
	v_mul_f32_e32 v138, v98, v106
	v_mul_f32_e32 v139, v99, v107
	ds_read_u16 v68, v56 offset:33664
	ds_read_u16 v76, v56 offset:15232
	ds_read_u16 v69, v56 offset:33936
	ds_read_u16 v77, v56 offset:15504
	ds_read_u16 v70, v56 offset:34208
	ds_read_u16 v78, v56 offset:15776
	ds_read_u16 v71, v56 offset:34480
	ds_read_u16 v79, v56 offset:16048
	ds_read_u16 v72, v56 offset:34752
	ds_read_u16 v80, v56 offset:16320
	ds_read_u16 v73, v56 offset:35024
	ds_read_u16 v81, v56 offset:16592
	ds_read_u16 v74, v56 offset:35296
	ds_read_u16 v82, v56 offset:16864
	ds_read_u16 v75, v56 offset:35568
	ds_read_u16 v83, v56 offset:17136
	s_waitcnt lgkmcnt(0)
	v_lshlrev_b32_e32 v84, 16, v68
	v_lshlrev_b32_e32 v85, 16, v69
	v_lshlrev_b32_e32 v86, 16, v70
	v_lshlrev_b32_e32 v87, 16, v71
	v_lshlrev_b32_e32 v88, 16, v72
	v_lshlrev_b32_e32 v89, 16, v73
	v_lshlrev_b32_e32 v90, 16, v74
	v_lshlrev_b32_e32 v91, 16, v75
	v_lshlrev_b32_e32 v100, 16, v76
	v_lshlrev_b32_e32 v101, 16, v77
	v_lshlrev_b32_e32 v102, 16, v78
	v_lshlrev_b32_e32 v103, 16, v79
	v_lshlrev_b32_e32 v104, 16, v80
	v_lshlrev_b32_e32 v105, 16, v81
	v_lshlrev_b32_e32 v106, 16, v82
	v_lshlrev_b32_e32 v107, 16, v83
	v_mul_f32_e32 v84, 0xbfb8aa3b, v84
	v_mul_f32_e32 v85, 0xbfb8aa3b, v85
	v_mul_f32_e32 v86, 0xbfb8aa3b, v86
	v_mul_f32_e32 v87, 0xbfb8aa3b, v87
	v_mul_f32_e32 v88, 0xbfb8aa3b, v88
	v_mul_f32_e32 v89, 0xbfb8aa3b, v89
	v_mul_f32_e32 v90, 0xbfb8aa3b, v90
	v_mul_f32_e32 v91, 0xbfb8aa3b, v91
	v_mul_f32_e32 v108, 0xbfb8aa3b, v100
	v_mul_f32_e32 v109, 0xbfb8aa3b, v101
	v_mul_f32_e32 v110, 0xbfb8aa3b, v102
	v_mul_f32_e32 v111, 0xbfb8aa3b, v103
	v_mul_f32_e32 v112, 0xbfb8aa3b, v104
	v_mul_f32_e32 v113, 0xbfb8aa3b, v105
	v_mul_f32_e32 v114, 0xbfb8aa3b, v106
	v_mul_f32_e32 v115, 0xbfb8aa3b, v107
	v_exp_f32_e32 v84, v84
	v_exp_f32_e32 v85, v85
	v_exp_f32_e32 v86, v86
	v_exp_f32_e32 v87, v87
	v_exp_f32_e32 v88, v88
	v_exp_f32_e32 v89, v89
	v_exp_f32_e32 v90, v90
	v_exp_f32_e32 v91, v91
	v_exp_f32_e32 v108, v108
	v_exp_f32_e32 v109, v109
	v_exp_f32_e32 v110, v110
	v_exp_f32_e32 v111, v111
	v_exp_f32_e32 v112, v112
	v_exp_f32_e32 v113, v113
	v_exp_f32_e32 v114, v114
	v_exp_f32_e32 v115, v115
	v_add_f32_e32 v84, 1.0, v84
	v_add_f32_e32 v85, 1.0, v85
	v_add_f32_e32 v86, 1.0, v86
	v_add_f32_e32 v87, 1.0, v87
	v_add_f32_e32 v88, 1.0, v88
	v_add_f32_e32 v89, 1.0, v89
	v_add_f32_e32 v90, 1.0, v90
	v_add_f32_e32 v91, 1.0, v91
	v_add_f32_e32 v108, 1.0, v108
	v_add_f32_e32 v109, 1.0, v109
	v_add_f32_e32 v110, 1.0, v110
	v_add_f32_e32 v111, 1.0, v111
	v_add_f32_e32 v112, 1.0, v112
	v_add_f32_e32 v113, 1.0, v113
	v_add_f32_e32 v114, 1.0, v114
	v_add_f32_e32 v115, 1.0, v115
	v_rcp_f32_e32 v84, v84
	v_rcp_f32_e32 v85, v85
	v_rcp_f32_e32 v86, v86
	v_rcp_f32_e32 v87, v87
	v_rcp_f32_e32 v88, v88
	v_rcp_f32_e32 v89, v89
	v_rcp_f32_e32 v90, v90
	v_rcp_f32_e32 v91, v91
	v_rcp_f32_e32 v108, v108
	v_rcp_f32_e32 v109, v109
	v_rcp_f32_e32 v110, v110
	v_rcp_f32_e32 v111, v111
	v_rcp_f32_e32 v112, v112
	v_rcp_f32_e32 v113, v113
	v_rcp_f32_e32 v114, v114
	v_rcp_f32_e32 v115, v115
	v_sub_f32_e32 v92, 1.0, v84
	v_sub_f32_e32 v93, 1.0, v85
	v_sub_f32_e32 v94, 1.0, v86
	v_sub_f32_e32 v95, 1.0, v87
	v_sub_f32_e32 v96, 1.0, v88
	v_sub_f32_e32 v97, 1.0, v89
	v_sub_f32_e32 v98, 1.0, v90
	v_sub_f32_e32 v99, 1.0, v91
	v_fma_f32 v84, v26, v84, v53
	v_fma_f32 v85, v26, v85, v53
	v_fma_f32 v86, v26, v86, v53
	v_fma_f32 v87, v26, v87, v53
	v_fma_f32 v88, v26, v88, v53
	v_fma_f32 v89, v26, v89, v53
	v_fma_f32 v90, v26, v90, v53
	v_fma_f32 v91, v26, v91, v53
	v_mul_f32_e32 v92, v26, v92
	v_mul_f32_e32 v93, v26, v93
	v_mul_f32_e32 v94, v26, v94
	v_mul_f32_e32 v95, v26, v95
	v_mul_f32_e32 v96, v26, v96
	v_mul_f32_e32 v97, v26, v97
	v_mul_f32_e32 v98, v26, v98
	v_mul_f32_e32 v99, v26, v99
	v_mul_f32_e32 v108, v108, v100
	v_mul_f32_e32 v109, v109, v101
	v_mul_f32_e32 v110, v110, v102
	v_mul_f32_e32 v111, v111, v103
	v_mul_f32_e32 v112, v112, v104
	v_mul_f32_e32 v113, v113, v105
	v_mul_f32_e32 v114, v114, v106
	v_mul_f32_e32 v115, v115, v107
	v_mul_f32_e32 v84, v27, v84
	v_mul_f32_e32 v85, v84, v85
	v_mul_f32_e32 v86, v85, v86
	v_mul_f32_e32 v87, v86, v87
	v_mul_f32_e32 v88, v87, v88
	v_mul_f32_e32 v89, v88, v89
	v_mul_f32_e32 v90, v89, v90
	v_mul_f32_e32 v91, v90, v91
	v_mov_b32_e32 v27, v91
	v_rcp_f32_e32 v100, v84
	v_rcp_f32_e32 v101, v85
	v_rcp_f32_e32 v102, v86
	v_rcp_f32_e32 v103, v87
	v_rcp_f32_e32 v104, v88
	v_rcp_f32_e32 v105, v89
	v_rcp_f32_e32 v106, v90
	v_rcp_f32_e32 v107, v91
	v_mul_f32_e32 v172, v84, v108
	v_mul_f32_e32 v173, v85, v109
	v_mul_f32_e32 v174, v86, v110
	v_mul_f32_e32 v175, v87, v111
	v_mul_f32_e32 v176, v88, v112
	v_mul_f32_e32 v177, v89, v113
	v_mul_f32_e32 v178, v90, v114
	v_mul_f32_e32 v179, v91, v115
	v_mul_f32_e32 v140, v92, v100
	v_mul_f32_e32 v141, v93, v101
	v_mul_f32_e32 v142, v94, v102
	v_mul_f32_e32 v143, v95, v103
	v_mul_f32_e32 v144, v96, v104
	v_mul_f32_e32 v145, v97, v105
	v_mul_f32_e32 v146, v98, v106
	v_mul_f32_e32 v147, v99, v107
	v_lshlrev_b32_e32 v84, 1, v56
	v_add_u32_e32 v84, 0x10000, v84
	s_barrier
	ds_read_b32 v85, v84 offset:0
	s_waitcnt lgkmcnt(0)
	v_rcp_f32_e32 v86, v85
	v_mul_f32_e32 v27, v85, v27
	ds_write_b32 v84, v27 offset:512
	v_mul_f32_e32 v116, v116, v86
	v_mul_f32_e32 v117, v117, v86
	v_mul_f32_e32 v118, v118, v86
	v_mul_f32_e32 v119, v119, v86
	v_mul_f32_e32 v120, v120, v86
	v_mul_f32_e32 v121, v121, v86
	v_mul_f32_e32 v122, v122, v86
	v_mul_f32_e32 v123, v123, v86
	v_mul_f32_e32 v124, v124, v86
	v_mul_f32_e32 v125, v125, v86
	v_mul_f32_e32 v126, v126, v86
	v_mul_f32_e32 v127, v127, v86
	v_mul_f32_e32 v128, v128, v86
	v_mul_f32_e32 v129, v129, v86
	v_mul_f32_e32 v130, v130, v86
	v_mul_f32_e32 v131, v131, v86
	v_mul_f32_e32 v132, v132, v86
	v_mul_f32_e32 v133, v133, v86
	v_mul_f32_e32 v134, v134, v86
	v_mul_f32_e32 v135, v135, v86
	v_mul_f32_e32 v136, v136, v86
	v_mul_f32_e32 v137, v137, v86
	v_mul_f32_e32 v138, v138, v86
	v_mul_f32_e32 v139, v139, v86
	v_mul_f32_e32 v140, v140, v86
	v_mul_f32_e32 v141, v141, v86
	v_mul_f32_e32 v142, v142, v86
	v_mul_f32_e32 v143, v143, v86
	v_mul_f32_e32 v144, v144, v86
	v_mul_f32_e32 v145, v145, v86
	v_mul_f32_e32 v146, v146, v86
	v_mul_f32_e32 v147, v147, v86
	v_mul_f32_e32 v148, v148, v85
	v_mul_f32_e32 v149, v149, v85
	v_mul_f32_e32 v150, v150, v85
	v_mul_f32_e32 v151, v151, v85
	v_mul_f32_e32 v152, v152, v85
	v_mul_f32_e32 v153, v153, v85
	v_mul_f32_e32 v154, v154, v85
	v_mul_f32_e32 v155, v155, v85
	v_mul_f32_e32 v156, v156, v85
	v_mul_f32_e32 v157, v157, v85
	v_mul_f32_e32 v158, v158, v85
	v_mul_f32_e32 v159, v159, v85
	v_mul_f32_e32 v160, v160, v85
	v_mul_f32_e32 v161, v161, v85
	v_mul_f32_e32 v162, v162, v85
	v_mul_f32_e32 v163, v163, v85
	v_mul_f32_e32 v164, v164, v85
	v_mul_f32_e32 v165, v165, v85
	v_mul_f32_e32 v166, v166, v85
	v_mul_f32_e32 v167, v167, v85
	v_mul_f32_e32 v168, v168, v85
	v_mul_f32_e32 v169, v169, v85
	v_mul_f32_e32 v170, v170, v85
	v_mul_f32_e32 v171, v171, v85
	v_mul_f32_e32 v172, v172, v85
	v_mul_f32_e32 v173, v173, v85
	v_mul_f32_e32 v174, v174, v85
	v_mul_f32_e32 v175, v175, v85
	v_mul_f32_e32 v176, v176, v85
	v_mul_f32_e32 v177, v177, v85
	v_mul_f32_e32 v178, v178, v85
	v_mul_f32_e32 v179, v179, v85
	v_cvt_pk_bf16_f32 v116, v116, v148
	v_cvt_pk_bf16_f32 v117, v117, v149
	v_cvt_pk_bf16_f32 v118, v118, v150
	v_cvt_pk_bf16_f32 v119, v119, v151
	v_cvt_pk_bf16_f32 v120, v120, v152
	v_cvt_pk_bf16_f32 v121, v121, v153
	v_cvt_pk_bf16_f32 v122, v122, v154
	v_cvt_pk_bf16_f32 v123, v123, v155
	v_cvt_pk_bf16_f32 v124, v124, v156
	v_cvt_pk_bf16_f32 v125, v125, v157
	v_cvt_pk_bf16_f32 v126, v126, v158
	v_cvt_pk_bf16_f32 v127, v127, v159
	v_cvt_pk_bf16_f32 v128, v128, v160
	v_cvt_pk_bf16_f32 v129, v129, v161
	v_cvt_pk_bf16_f32 v130, v130, v162
	v_cvt_pk_bf16_f32 v131, v131, v163
	v_cvt_pk_bf16_f32 v132, v132, v164
	v_cvt_pk_bf16_f32 v133, v133, v165
	v_cvt_pk_bf16_f32 v134, v134, v166
	v_cvt_pk_bf16_f32 v135, v135, v167
	v_cvt_pk_bf16_f32 v136, v136, v168
	v_cvt_pk_bf16_f32 v137, v137, v169
	v_cvt_pk_bf16_f32 v138, v138, v170
	v_cvt_pk_bf16_f32 v139, v139, v171
	v_cvt_pk_bf16_f32 v140, v140, v172
	v_cvt_pk_bf16_f32 v141, v141, v173
	v_cvt_pk_bf16_f32 v142, v142, v174
	v_cvt_pk_bf16_f32 v143, v143, v175
	v_cvt_pk_bf16_f32 v144, v144, v176
	v_cvt_pk_bf16_f32 v145, v145, v177
	v_cvt_pk_bf16_f32 v146, v146, v178
	v_cvt_pk_bf16_f32 v147, v147, v179
	ds_write_b16_d16_hi v56, v116 offset:8704
	ds_write_b16 v56, v116 offset:27136
	ds_write_b16_d16_hi v56, v117 offset:8976
	ds_write_b16 v56, v117 offset:27408
	ds_write_b16_d16_hi v56, v118 offset:9248
	ds_write_b16 v56, v118 offset:27680
	ds_write_b16_d16_hi v56, v119 offset:9520
	ds_write_b16 v56, v119 offset:27952
	ds_write_b16_d16_hi v56, v120 offset:9792
	ds_write_b16 v56, v120 offset:28224
	ds_write_b16_d16_hi v56, v121 offset:10064
	ds_write_b16 v56, v121 offset:28496
	ds_write_b16_d16_hi v56, v122 offset:10336
	ds_write_b16 v56, v122 offset:28768
	ds_write_b16_d16_hi v56, v123 offset:10608
	ds_write_b16 v56, v123 offset:29040
	ds_write_b16_d16_hi v56, v124 offset:10880
	ds_write_b16 v56, v124 offset:29312
	ds_write_b16_d16_hi v56, v125 offset:11152
	ds_write_b16 v56, v125 offset:29584
	ds_write_b16_d16_hi v56, v126 offset:11424
	ds_write_b16 v56, v126 offset:29856
	ds_write_b16_d16_hi v56, v127 offset:11696
	ds_write_b16 v56, v127 offset:30128
	ds_write_b16_d16_hi v56, v128 offset:11968
	ds_write_b16 v56, v128 offset:30400
	ds_write_b16_d16_hi v56, v129 offset:12240
	ds_write_b16 v56, v129 offset:30672
	ds_write_b16_d16_hi v56, v130 offset:12512
	ds_write_b16 v56, v130 offset:30944
	ds_write_b16_d16_hi v56, v131 offset:12784
	ds_write_b16 v56, v131 offset:31216
	ds_write_b16_d16_hi v56, v132 offset:13056
	ds_write_b16 v56, v132 offset:31488
	ds_write_b16_d16_hi v56, v133 offset:13328
	ds_write_b16 v56, v133 offset:31760
	ds_write_b16_d16_hi v56, v134 offset:13600
	ds_write_b16 v56, v134 offset:32032
	ds_write_b16_d16_hi v56, v135 offset:13872
	ds_write_b16 v56, v135 offset:32304
	ds_write_b16_d16_hi v56, v136 offset:14144
	ds_write_b16 v56, v136 offset:32576
	ds_write_b16_d16_hi v56, v137 offset:14416
	ds_write_b16 v56, v137 offset:32848
	ds_write_b16_d16_hi v56, v138 offset:14688
	ds_write_b16 v56, v138 offset:33120
	ds_write_b16_d16_hi v56, v139 offset:14960
	ds_write_b16 v56, v139 offset:33392
	ds_write_b16_d16_hi v56, v140 offset:15232
	ds_write_b16 v56, v140 offset:33664
	ds_write_b16_d16_hi v56, v141 offset:15504
	ds_write_b16 v56, v141 offset:33936
	ds_write_b16_d16_hi v56, v142 offset:15776
	ds_write_b16 v56, v142 offset:34208
	ds_write_b16_d16_hi v56, v143 offset:16048
	ds_write_b16 v56, v143 offset:34480
	ds_write_b16_d16_hi v56, v144 offset:16320
	ds_write_b16 v56, v144 offset:34752
	ds_write_b16_d16_hi v56, v145 offset:16592
	ds_write_b16 v56, v145 offset:35024
	ds_write_b16_d16_hi v56, v146 offset:16864
	ds_write_b16 v56, v146 offset:35296
	ds_write_b16_d16_hi v56, v147 offset:17136
	ds_write_b16 v56, v147 offset:35568
	s_waitcnt lgkmcnt(0)
	s_barrier
	v_mov_b32_e32 v27, 0
	s_branch .Lhp_join2
.Lhp_join:
	s_ashr_i32 s15, s14, 31
	s_lshl_b64 s[24:25], s[14:15], 9
	s_add_u32 s24, s37, s24
	s_addc_u32 s25, s38, s25
	v_lshlrev_b32_e32 v84, 1, v56
	global_store_dword v84, v27, s[24:25]
.Lhp_join2:
	s_ashr_i32 s15, s14, 31
	v_mov_b64_e32 v[58:59], s[14:15]
	v_lshlrev_b32_e32 v56, 1, v52
	s_mov_b64 s[0:1], 0
	v_cmp_gt_i32_e32 vcc, s34, v52
	s_branch .LBB0_901
.Lhp_keep:
	s_and_saveexec_b64 s[24:25], s[0:1]
	s_xor_b64 s[0:1], exec, s[24:25]
	s_ashr_i32 s15, s14, 31
	s_or_saveexec_b64 s[0:1], s[0:1]
	v_mov_b32_e32 v27, 0
	v_mov_b64_e32 v[58:59], s[14:15]
	v_lshlrev_b32_e32 v56, 1, v52
	s_xor_b64 exec, exec, s[0:1]
	s_cbranch_execz .LBB0_901
	v_sub_f32_e32 v26, v60, v53
	v_mul_f32_e32 v26, 0xbfb8aa3b, v26
	v_exp_f32_e32 v26, v26
	s_cmpk_gt_i32 s33, 0x1ff
	s_cselect_b32 s15, 16, 64
	ds_read_u16 v68, v56 offset:18432
	ds_read_u16 v76, v56
	ds_read_u16 v69, v56 offset:18704
	ds_read_u16 v77, v56 offset:272
	ds_read_u16 v70, v56 offset:18976
	ds_read_u16 v78, v56 offset:544
	ds_read_u16 v71, v56 offset:19248
	ds_read_u16 v79, v56 offset:816
	ds_read_u16 v72, v56 offset:19520
	ds_read_u16 v80, v56 offset:1088
	ds_read_u16 v73, v56 offset:19792
	ds_read_u16 v81, v56 offset:1360
	ds_read_u16 v74, v56 offset:20064
	ds_read_u16 v82, v56 offset:1632
	ds_read_u16 v75, v56 offset:20336
	ds_read_u16 v83, v56 offset:1904
	v_add_f32_e32 v26, 1.0, v26
	v_rcp_f32_e32 v53, v26
	v_mov_b32_e32 v27, 1.0
	s_nop 0
	v_sub_f32_e32 v26, 1.0, v53
	s_waitcnt lgkmcnt(0)
	v_lshlrev_b32_e32 v84, 16, v68
	v_lshlrev_b32_e32 v85, 16, v69
	v_lshlrev_b32_e32 v86, 16, v70
	v_lshlrev_b32_e32 v87, 16, v71
	v_lshlrev_b32_e32 v88, 16, v72
	v_lshlrev_b32_e32 v89, 16, v73
	v_lshlrev_b32_e32 v90, 16, v74
	v_lshlrev_b32_e32 v91, 16, v75
	v_lshlrev_b32_e32 v100, 16, v76
	v_lshlrev_b32_e32 v101, 16, v77
	v_lshlrev_b32_e32 v102, 16, v78
	v_lshlrev_b32_e32 v103, 16, v79
	v_lshlrev_b32_e32 v104, 16, v80
	v_lshlrev_b32_e32 v105, 16, v81
	v_lshlrev_b32_e32 v106, 16, v82
	v_lshlrev_b32_e32 v107, 16, v83
	ds_read_u16 v116, v56 offset:20608
	ds_read_u16 v124, v56 offset:2176
	ds_read_u16 v117, v56 offset:20880
	ds_read_u16 v125, v56 offset:2448
	ds_read_u16 v118, v56 offset:21152
	ds_read_u16 v126, v56 offset:2720
	ds_read_u16 v119, v56 offset:21424
	ds_read_u16 v127, v56 offset:2992
	ds_read_u16 v120, v56 offset:21696
	ds_read_u16 v128, v56 offset:3264
	ds_read_u16 v121, v56 offset:21968
	ds_read_u16 v129, v56 offset:3536
	ds_read_u16 v122, v56 offset:22240
	ds_read_u16 v130, v56 offset:3808
	ds_read_u16 v123, v56 offset:22512
	ds_read_u16 v131, v56 offset:4080
	v_mul_f32_e32 v84, 0xbfb8aa3b, v84
	v_mul_f32_e32 v85, 0xbfb8aa3b, v85
	v_mul_f32_e32 v86, 0xbfb8aa3b, v86
	v_mul_f32_e32 v87, 0xbfb8aa3b, v87
	v_mul_f32_e32 v88, 0xbfb8aa3b, v88
	v_mul_f32_e32 v89, 0xbfb8aa3b, v89
	v_mul_f32_e32 v90, 0xbfb8aa3b, v90
	v_mul_f32_e32 v91, 0xbfb8aa3b, v91
	v_mul_f32_e32 v108, 0xbfb8aa3b, v100
	v_mul_f32_e32 v109, 0xbfb8aa3b, v101
	v_mul_f32_e32 v110, 0xbfb8aa3b, v102
	v_mul_f32_e32 v111, 0xbfb8aa3b, v103
	v_mul_f32_e32 v112, 0xbfb8aa3b, v104
	v_mul_f32_e32 v113, 0xbfb8aa3b, v105
	v_mul_f32_e32 v114, 0xbfb8aa3b, v106
	v_mul_f32_e32 v115, 0xbfb8aa3b, v107
	v_exp_f32_e32 v84, v84
	v_exp_f32_e32 v85, v85
	v_exp_f32_e32 v86, v86
	v_exp_f32_e32 v87, v87
	v_exp_f32_e32 v88, v88
	v_exp_f32_e32 v89, v89
	v_exp_f32_e32 v90, v90
	v_exp_f32_e32 v91, v91
	v_exp_f32_e32 v108, v108
	v_exp_f32_e32 v109, v109
	v_exp_f32_e32 v110, v110
	v_exp_f32_e32 v111, v111
	v_exp_f32_e32 v112, v112
	v_exp_f32_e32 v113, v113
	v_exp_f32_e32 v114, v114
	v_exp_f32_e32 v115, v115
	v_add_f32_e32 v84, 1.0, v84
	v_add_f32_e32 v85, 1.0, v85
	v_add_f32_e32 v86, 1.0, v86
	v_add_f32_e32 v87, 1.0, v87
	v_add_f32_e32 v88, 1.0, v88
	v_add_f32_e32 v89, 1.0, v89
	v_add_f32_e32 v90, 1.0, v90
	v_add_f32_e32 v91, 1.0, v91
	v_add_f32_e32 v108, 1.0, v108
	v_add_f32_e32 v109, 1.0, v109
	v_add_f32_e32 v110, 1.0, v110
	v_add_f32_e32 v111, 1.0, v111
	v_add_f32_e32 v112, 1.0, v112
	v_add_f32_e32 v113, 1.0, v113
	v_add_f32_e32 v114, 1.0, v114
	v_add_f32_e32 v115, 1.0, v115
	v_rcp_f32_e32 v84, v84
	v_rcp_f32_e32 v85, v85
	v_rcp_f32_e32 v86, v86
	v_rcp_f32_e32 v87, v87
	v_rcp_f32_e32 v88, v88
	v_rcp_f32_e32 v89, v89
	v_rcp_f32_e32 v90, v90
	v_rcp_f32_e32 v91, v91
	v_rcp_f32_e32 v108, v108
	v_rcp_f32_e32 v109, v109
	v_rcp_f32_e32 v110, v110
	v_rcp_f32_e32 v111, v111
	v_rcp_f32_e32 v112, v112
	v_rcp_f32_e32 v113, v113
	v_rcp_f32_e32 v114, v114
	v_rcp_f32_e32 v115, v115
	v_sub_f32_e32 v92, 1.0, v84
	v_sub_f32_e32 v93, 1.0, v85
	v_sub_f32_e32 v94, 1.0, v86
	v_sub_f32_e32 v95, 1.0, v87
	v_sub_f32_e32 v96, 1.0, v88
	v_sub_f32_e32 v97, 1.0, v89
	v_sub_f32_e32 v98, 1.0, v90
	v_sub_f32_e32 v99, 1.0, v91
	v_fma_f32 v84, v26, v84, v53
	v_fma_f32 v85, v26, v85, v53
	v_fma_f32 v86, v26, v86, v53
	v_fma_f32 v87, v26, v87, v53
	v_fma_f32 v88, v26, v88, v53
	v_fma_f32 v89, v26, v89, v53
	v_fma_f32 v90, v26, v90, v53
	v_fma_f32 v91, v26, v91, v53
	v_mul_f32_e32 v92, v26, v92
	v_mul_f32_e32 v93, v26, v93
	v_mul_f32_e32 v94, v26, v94
	v_mul_f32_e32 v95, v26, v95
	v_mul_f32_e32 v96, v26, v96
	v_mul_f32_e32 v97, v26, v97
	v_mul_f32_e32 v98, v26, v98
	v_mul_f32_e32 v99, v26, v99
	v_mul_f32_e32 v108, v108, v100
	v_mul_f32_e32 v109, v109, v101
	v_mul_f32_e32 v110, v110, v102
	v_mul_f32_e32 v111, v111, v103
	v_mul_f32_e32 v112, v112, v104
	v_mul_f32_e32 v113, v113, v105
	v_mul_f32_e32 v114, v114, v106
	v_mul_f32_e32 v115, v115, v107
	v_mul_f32_e32 v84, v27, v84
	v_mul_f32_e32 v85, v84, v85
	v_mul_f32_e32 v86, v85, v86
	v_mul_f32_e32 v87, v86, v87
	v_mul_f32_e32 v88, v87, v88
	v_mul_f32_e32 v89, v88, v89
	v_mul_f32_e32 v90, v89, v90
	v_mul_f32_e32 v91, v90, v91
	v_mov_b32_e32 v27, v91
	v_rcp_f32_e32 v100, v84
	v_rcp_f32_e32 v101, v85
	v_rcp_f32_e32 v102, v86
	v_rcp_f32_e32 v103, v87
	v_rcp_f32_e32 v104, v88
	v_rcp_f32_e32 v105, v89
	v_rcp_f32_e32 v106, v90
	v_rcp_f32_e32 v107, v91
	v_mul_f32_e32 v108, v84, v108
	v_mul_f32_e32 v109, v85, v109
	v_mul_f32_e32 v110, v86, v110
	v_mul_f32_e32 v111, v87, v111
	v_mul_f32_e32 v112, v88, v112
	v_mul_f32_e32 v113, v89, v113
	v_mul_f32_e32 v114, v90, v114
	v_mul_f32_e32 v115, v91, v115
	v_mul_f32_e32 v92, v92, v100
	v_mul_f32_e32 v93, v93, v101
	v_mul_f32_e32 v94, v94, v102
	v_mul_f32_e32 v95, v95, v103
	v_mul_f32_e32 v96, v96, v104
	v_mul_f32_e32 v97, v97, v105
	v_mul_f32_e32 v98, v98, v106
	v_mul_f32_e32 v99, v99, v107
	v_cvt_pk_bf16_f32 v92, v92, v108
	v_cvt_pk_bf16_f32 v93, v93, v109
	v_cvt_pk_bf16_f32 v94, v94, v110
	v_cvt_pk_bf16_f32 v95, v95, v111
	v_cvt_pk_bf16_f32 v96, v96, v112
	v_cvt_pk_bf16_f32 v97, v97, v113
	v_cvt_pk_bf16_f32 v98, v98, v114
	v_cvt_pk_bf16_f32 v99, v99, v115
	s_waitcnt lgkmcnt(0)
	ds_write_b16_d16_hi v56, v92
	ds_write_b16 v56, v92 offset:18432
	ds_write_b16_d16_hi v56, v93 offset:272
	ds_write_b16 v56, v93 offset:18704
	ds_write_b16_d16_hi v56, v94 offset:544
	ds_write_b16 v56, v94 offset:18976
	ds_write_b16_d16_hi v56, v95 offset:816
	ds_write_b16 v56, v95 offset:19248
	ds_write_b16_d16_hi v56, v96 offset:1088
	ds_write_b16 v56, v96 offset:19520
	ds_write_b16_d16_hi v56, v97 offset:1360
	ds_write_b16 v56, v97 offset:19792
	ds_write_b16_d16_hi v56, v98 offset:1632
	ds_write_b16 v56, v98 offset:20064
	ds_write_b16_d16_hi v56, v99 offset:1904
	ds_write_b16 v56, v99 offset:20336
	v_lshlrev_b32_e32 v84, 16, v116
	v_lshlrev_b32_e32 v85, 16, v117
	v_lshlrev_b32_e32 v86, 16, v118
	v_lshlrev_b32_e32 v87, 16, v119
	v_lshlrev_b32_e32 v88, 16, v120
	v_lshlrev_b32_e32 v89, 16, v121
	v_lshlrev_b32_e32 v90, 16, v122
	v_lshlrev_b32_e32 v91, 16, v123
	v_lshlrev_b32_e32 v100, 16, v124
	v_lshlrev_b32_e32 v101, 16, v125
	v_lshlrev_b32_e32 v102, 16, v126
	v_lshlrev_b32_e32 v103, 16, v127
	v_lshlrev_b32_e32 v104, 16, v128
	v_lshlrev_b32_e32 v105, 16, v129
	v_lshlrev_b32_e32 v106, 16, v130
	v_lshlrev_b32_e32 v107, 16, v131
	ds_read_u16 v68, v56 offset:22784
	ds_read_u16 v76, v56 offset:4352
	ds_read_u16 v69, v56 offset:23056
	ds_read_u16 v77, v56 offset:4624
	ds_read_u16 v70, v56 offset:23328
	ds_read_u16 v78, v56 offset:4896
	ds_read_u16 v71, v56 offset:23600
	ds_read_u16 v79, v56 offset:5168
	ds_read_u16 v72, v56 offset:23872
	ds_read_u16 v80, v56 offset:5440
	ds_read_u16 v73, v56 offset:24144
	ds_read_u16 v81, v56 offset:5712
	ds_read_u16 v74, v56 offset:24416
	ds_read_u16 v82, v56 offset:5984
	ds_read_u16 v75, v56 offset:24688
	ds_read_u16 v83, v56 offset:6256
	v_mul_f32_e32 v84, 0xbfb8aa3b, v84
	v_mul_f32_e32 v85, 0xbfb8aa3b, v85
	v_mul_f32_e32 v86, 0xbfb8aa3b, v86
	v_mul_f32_e32 v87, 0xbfb8aa3b, v87
	v_mul_f32_e32 v88, 0xbfb8aa3b, v88
	v_mul_f32_e32 v89, 0xbfb8aa3b, v89
	v_mul_f32_e32 v90, 0xbfb8aa3b, v90
	v_mul_f32_e32 v91, 0xbfb8aa3b, v91
	v_mul_f32_e32 v108, 0xbfb8aa3b, v100
	v_mul_f32_e32 v109, 0xbfb8aa3b, v101
	v_mul_f32_e32 v110, 0xbfb8aa3b, v102
	v_mul_f32_e32 v111, 0xbfb8aa3b, v103
	v_mul_f32_e32 v112, 0xbfb8aa3b, v104
	v_mul_f32_e32 v113, 0xbfb8aa3b, v105
	v_mul_f32_e32 v114, 0xbfb8aa3b, v106
	v_mul_f32_e32 v115, 0xbfb8aa3b, v107
	v_exp_f32_e32 v84, v84
	v_exp_f32_e32 v85, v85
	v_exp_f32_e32 v86, v86
	v_exp_f32_e32 v87, v87
	v_exp_f32_e32 v88, v88
	v_exp_f32_e32 v89, v89
	v_exp_f32_e32 v90, v90
	v_exp_f32_e32 v91, v91
	v_exp_f32_e32 v108, v108
	v_exp_f32_e32 v109, v109
	v_exp_f32_e32 v110, v110
	v_exp_f32_e32 v111, v111
	v_exp_f32_e32 v112, v112
	v_exp_f32_e32 v113, v113
	v_exp_f32_e32 v114, v114
	v_exp_f32_e32 v115, v115
	v_add_f32_e32 v84, 1.0, v84
	v_add_f32_e32 v85, 1.0, v85
	v_add_f32_e32 v86, 1.0, v86
	v_add_f32_e32 v87, 1.0, v87
	v_add_f32_e32 v88, 1.0, v88
	v_add_f32_e32 v89, 1.0, v89
	v_add_f32_e32 v90, 1.0, v90
	v_add_f32_e32 v91, 1.0, v91
	v_add_f32_e32 v108, 1.0, v108
	v_add_f32_e32 v109, 1.0, v109
	v_add_f32_e32 v110, 1.0, v110
	v_add_f32_e32 v111, 1.0, v111
	v_add_f32_e32 v112, 1.0, v112
	v_add_f32_e32 v113, 1.0, v113
	v_add_f32_e32 v114, 1.0, v114
	v_add_f32_e32 v115, 1.0, v115
	v_rcp_f32_e32 v84, v84
	v_rcp_f32_e32 v85, v85
	v_rcp_f32_e32 v86, v86
	v_rcp_f32_e32 v87, v87
	v_rcp_f32_e32 v88, v88
	v_rcp_f32_e32 v89, v89
	v_rcp_f32_e32 v90, v90
	v_rcp_f32_e32 v91, v91
	v_rcp_f32_e32 v108, v108
	v_rcp_f32_e32 v109, v109
	v_rcp_f32_e32 v110, v110
	v_rcp_f32_e32 v111, v111
	v_rcp_f32_e32 v112, v112
	v_rcp_f32_e32 v113, v113
	v_rcp_f32_e32 v114, v114
	v_rcp_f32_e32 v115, v115
	v_sub_f32_e32 v92, 1.0, v84
	v_sub_f32_e32 v93, 1.0, v85
	v_sub_f32_e32 v94, 1.0, v86
	v_sub_f32_e32 v95, 1.0, v87
	v_sub_f32_e32 v96, 1.0, v88
	v_sub_f32_e32 v97, 1.0, v89
	v_sub_f32_e32 v98, 1.0, v90
	v_sub_f32_e32 v99, 1.0, v91
	v_fma_f32 v84, v26, v84, v53
	v_fma_f32 v85, v26, v85, v53
	v_fma_f32 v86, v26, v86, v53
	v_fma_f32 v87, v26, v87, v53
	v_fma_f32 v88, v26, v88, v53
	v_fma_f32 v89, v26, v89, v53
	v_fma_f32 v90, v26, v90, v53
	v_fma_f32 v91, v26, v91, v53
	v_mul_f32_e32 v92, v26, v92
	v_mul_f32_e32 v93, v26, v93
	v_mul_f32_e32 v94, v26, v94
	v_mul_f32_e32 v95, v26, v95
	v_mul_f32_e32 v96, v26, v96
	v_mul_f32_e32 v97, v26, v97
	v_mul_f32_e32 v98, v26, v98
	v_mul_f32_e32 v99, v26, v99
	v_mul_f32_e32 v108, v108, v100
	v_mul_f32_e32 v109, v109, v101
	v_mul_f32_e32 v110, v110, v102
	v_mul_f32_e32 v111, v111, v103
	v_mul_f32_e32 v112, v112, v104
	v_mul_f32_e32 v113, v113, v105
	v_mul_f32_e32 v114, v114, v106
	v_mul_f32_e32 v115, v115, v107
	v_mul_f32_e32 v84, v27, v84
	v_mul_f32_e32 v85, v84, v85
	v_mul_f32_e32 v86, v85, v86
	v_mul_f32_e32 v87, v86, v87
	v_mul_f32_e32 v88, v87, v88
	v_mul_f32_e32 v89, v88, v89
	v_mul_f32_e32 v90, v89, v90
	v_mul_f32_e32 v91, v90, v91
	v_mov_b32_e32 v27, v91
	v_rcp_f32_e32 v100, v84
	v_rcp_f32_e32 v101, v85
	v_rcp_f32_e32 v102, v86
	v_rcp_f32_e32 v103, v87
	v_rcp_f32_e32 v104, v88
	v_rcp_f32_e32 v105, v89
	v_rcp_f32_e32 v106, v90
	v_rcp_f32_e32 v107, v91
	v_mul_f32_e32 v108, v84, v108
	v_mul_f32_e32 v109, v85, v109
	v_mul_f32_e32 v110, v86, v110
	v_mul_f32_e32 v111, v87, v111
	v_mul_f32_e32 v112, v88, v112
	v_mul_f32_e32 v113, v89, v113
	v_mul_f32_e32 v114, v90, v114
	v_mul_f32_e32 v115, v91, v115
	v_mul_f32_e32 v92, v92, v100
	v_mul_f32_e32 v93, v93, v101
	v_mul_f32_e32 v94, v94, v102
	v_mul_f32_e32 v95, v95, v103
	v_mul_f32_e32 v96, v96, v104
	v_mul_f32_e32 v97, v97, v105
	v_mul_f32_e32 v98, v98, v106
	v_mul_f32_e32 v99, v99, v107
	v_cvt_pk_bf16_f32 v92, v92, v108
	v_cvt_pk_bf16_f32 v93, v93, v109
	v_cvt_pk_bf16_f32 v94, v94, v110
	v_cvt_pk_bf16_f32 v95, v95, v111
	v_cvt_pk_bf16_f32 v96, v96, v112
	v_cvt_pk_bf16_f32 v97, v97, v113
	v_cvt_pk_bf16_f32 v98, v98, v114
	v_cvt_pk_bf16_f32 v99, v99, v115
	s_waitcnt lgkmcnt(0)
	ds_write_b16_d16_hi v56, v92 offset:2176
	ds_write_b16 v56, v92 offset:20608
	ds_write_b16_d16_hi v56, v93 offset:2448
	ds_write_b16 v56, v93 offset:20880
	ds_write_b16_d16_hi v56, v94 offset:2720
	ds_write_b16 v56, v94 offset:21152
	ds_write_b16_d16_hi v56, v95 offset:2992
	ds_write_b16 v56, v95 offset:21424
	ds_write_b16_d16_hi v56, v96 offset:3264
	ds_write_b16 v56, v96 offset:21696
	ds_write_b16_d16_hi v56, v97 offset:3536
	ds_write_b16 v56, v97 offset:21968
	ds_write_b16_d16_hi v56, v98 offset:3808
	ds_write_b16 v56, v98 offset:22240
	ds_write_b16_d16_hi v56, v99 offset:4080
	ds_write_b16 v56, v99 offset:22512
	s_cmp_eq_u32 s15, 16
	s_cbranch_scc1 .Lhp_zero
	v_lshlrev_b32_e32 v84, 16, v68
	v_lshlrev_b32_e32 v85, 16, v69
	v_lshlrev_b32_e32 v86, 16, v70
	v_lshlrev_b32_e32 v87, 16, v71
	v_lshlrev_b32_e32 v88, 16, v72
	v_lshlrev_b32_e32 v89, 16, v73
	v_lshlrev_b32_e32 v90, 16, v74
	v_lshlrev_b32_e32 v91, 16, v75
	v_lshlrev_b32_e32 v100, 16, v76
	v_lshlrev_b32_e32 v101, 16, v77
	v_lshlrev_b32_e32 v102, 16, v78
	v_lshlrev_b32_e32 v103, 16, v79
	v_lshlrev_b32_e32 v104, 16, v80
	v_lshlrev_b32_e32 v105, 16, v81
	v_lshlrev_b32_e32 v106, 16, v82
	v_lshlrev_b32_e32 v107, 16, v83
	ds_read_u16 v116, v56 offset:24960
	ds_read_u16 v124, v56 offset:6528
	ds_read_u16 v117, v56 offset:25232
	ds_read_u16 v125, v56 offset:6800
	ds_read_u16 v118, v56 offset:25504
	ds_read_u16 v126, v56 offset:7072
	ds_read_u16 v119, v56 offset:25776
	ds_read_u16 v127, v56 offset:7344
	ds_read_u16 v120, v56 offset:26048
	ds_read_u16 v128, v56 offset:7616
	ds_read_u16 v121, v56 offset:26320
	ds_read_u16 v129, v56 offset:7888
	ds_read_u16 v122, v56 offset:26592
	ds_read_u16 v130, v56 offset:8160
	ds_read_u16 v123, v56 offset:26864
	ds_read_u16 v131, v56 offset:8432
	v_mul_f32_e32 v84, 0xbfb8aa3b, v84
	v_mul_f32_e32 v85, 0xbfb8aa3b, v85
	v_mul_f32_e32 v86, 0xbfb8aa3b, v86
	v_mul_f32_e32 v87, 0xbfb8aa3b, v87
	v_mul_f32_e32 v88, 0xbfb8aa3b, v88
	v_mul_f32_e32 v89, 0xbfb8aa3b, v89
	v_mul_f32_e32 v90, 0xbfb8aa3b, v90
	v_mul_f32_e32 v91, 0xbfb8aa3b, v91
	v_mul_f32_e32 v108, 0xbfb8aa3b, v100
	v_mul_f32_e32 v109, 0xbfb8aa3b, v101
	v_mul_f32_e32 v110, 0xbfb8aa3b, v102
	v_mul_f32_e32 v111, 0xbfb8aa3b, v103
	v_mul_f32_e32 v112, 0xbfb8aa3b, v104
	v_mul_f32_e32 v113, 0xbfb8aa3b, v105
	v_mul_f32_e32 v114, 0xbfb8aa3b, v106
	v_mul_f32_e32 v115, 0xbfb8aa3b, v107
	v_exp_f32_e32 v84, v84
	v_exp_f32_e32 v85, v85
	v_exp_f32_e32 v86, v86
	v_exp_f32_e32 v87, v87
	v_exp_f32_e32 v88, v88
	v_exp_f32_e32 v89, v89
	v_exp_f32_e32 v90, v90
	v_exp_f32_e32 v91, v91
	v_exp_f32_e32 v108, v108
	v_exp_f32_e32 v109, v109
	v_exp_f32_e32 v110, v110
	v_exp_f32_e32 v111, v111
	v_exp_f32_e32 v112, v112
	v_exp_f32_e32 v113, v113
	v_exp_f32_e32 v114, v114
	v_exp_f32_e32 v115, v115
	v_add_f32_e32 v84, 1.0, v84
	v_add_f32_e32 v85, 1.0, v85
	v_add_f32_e32 v86, 1.0, v86
	v_add_f32_e32 v87, 1.0, v87
	v_add_f32_e32 v88, 1.0, v88
	v_add_f32_e32 v89, 1.0, v89
	v_add_f32_e32 v90, 1.0, v90
	v_add_f32_e32 v91, 1.0, v91
	v_add_f32_e32 v108, 1.0, v108
	v_add_f32_e32 v109, 1.0, v109
	v_add_f32_e32 v110, 1.0, v110
	v_add_f32_e32 v111, 1.0, v111
	v_add_f32_e32 v112, 1.0, v112
	v_add_f32_e32 v113, 1.0, v113
	v_add_f32_e32 v114, 1.0, v114
	v_add_f32_e32 v115, 1.0, v115
	v_rcp_f32_e32 v84, v84
	v_rcp_f32_e32 v85, v85
	v_rcp_f32_e32 v86, v86
	v_rcp_f32_e32 v87, v87
	v_rcp_f32_e32 v88, v88
	v_rcp_f32_e32 v89, v89
	v_rcp_f32_e32 v90, v90
	v_rcp_f32_e32 v91, v91
	v_rcp_f32_e32 v108, v108
	v_rcp_f32_e32 v109, v109
	v_rcp_f32_e32 v110, v110
	v_rcp_f32_e32 v111, v111
	v_rcp_f32_e32 v112, v112
	v_rcp_f32_e32 v113, v113
	v_rcp_f32_e32 v114, v114
	v_rcp_f32_e32 v115, v115
	v_sub_f32_e32 v92, 1.0, v84
	v_sub_f32_e32 v93, 1.0, v85
	v_sub_f32_e32 v94, 1.0, v86
	v_sub_f32_e32 v95, 1.0, v87
	v_sub_f32_e32 v96, 1.0, v88
	v_sub_f32_e32 v97, 1.0, v89
	v_sub_f32_e32 v98, 1.0, v90
	v_sub_f32_e32 v99, 1.0, v91
	v_fma_f32 v84, v26, v84, v53
	v_fma_f32 v85, v26, v85, v53
	v_fma_f32 v86, v26, v86, v53
	v_fma_f32 v87, v26, v87, v53
	v_fma_f32 v88, v26, v88, v53
	v_fma_f32 v89, v26, v89, v53
	v_fma_f32 v90, v26, v90, v53
	v_fma_f32 v91, v26, v91, v53
	v_mul_f32_e32 v92, v26, v92
	v_mul_f32_e32 v93, v26, v93
	v_mul_f32_e32 v94, v26, v94
	v_mul_f32_e32 v95, v26, v95
	v_mul_f32_e32 v96, v26, v96
	v_mul_f32_e32 v97, v26, v97
	v_mul_f32_e32 v98, v26, v98
	v_mul_f32_e32 v99, v26, v99
	v_mul_f32_e32 v108, v108, v100
	v_mul_f32_e32 v109, v109, v101
	v_mul_f32_e32 v110, v110, v102
	v_mul_f32_e32 v111, v111, v103
	v_mul_f32_e32 v112, v112, v104
	v_mul_f32_e32 v113, v113, v105
	v_mul_f32_e32 v114, v114, v106
	v_mul_f32_e32 v115, v115, v107
	v_mul_f32_e32 v84, v27, v84
	v_mul_f32_e32 v85, v84, v85
	v_mul_f32_e32 v86, v85, v86
	v_mul_f32_e32 v87, v86, v87
	v_mul_f32_e32 v88, v87, v88
	v_mul_f32_e32 v89, v88, v89
	v_mul_f32_e32 v90, v89, v90
	v_mul_f32_e32 v91, v90, v91
	v_mov_b32_e32 v27, v91
	v_rcp_f32_e32 v100, v84
	v_rcp_f32_e32 v101, v85
	v_rcp_f32_e32 v102, v86
	v_rcp_f32_e32 v103, v87
	v_rcp_f32_e32 v104, v88
	v_rcp_f32_e32 v105, v89
	v_rcp_f32_e32 v106, v90
	v_rcp_f32_e32 v107, v91
	v_mul_f32_e32 v108, v84, v108
	v_mul_f32_e32 v109, v85, v109
	v_mul_f32_e32 v110, v86, v110
	v_mul_f32_e32 v111, v87, v111
	v_mul_f32_e32 v112, v88, v112
	v_mul_f32_e32 v113, v89, v113
	v_mul_f32_e32 v114, v90, v114
	v_mul_f32_e32 v115, v91, v115
	v_mul_f32_e32 v92, v92, v100
	v_mul_f32_e32 v93, v93, v101
	v_mul_f32_e32 v94, v94, v102
	v_mul_f32_e32 v95, v95, v103
	v_mul_f32_e32 v96, v96, v104
	v_mul_f32_e32 v97, v97, v105
	v_mul_f32_e32 v98, v98, v106
	v_mul_f32_e32 v99, v99, v107
	v_cvt_pk_bf16_f32 v92, v92, v108
	v_cvt_pk_bf16_f32 v93, v93, v109
	v_cvt_pk_bf16_f32 v94, v94, v110
	v_cvt_pk_bf16_f32 v95, v95, v111
	v_cvt_pk_bf16_f32 v96, v96, v112
	v_cvt_pk_bf16_f32 v97, v97, v113
	v_cvt_pk_bf16_f32 v98, v98, v114
	v_cvt_pk_bf16_f32 v99, v99, v115
	s_waitcnt lgkmcnt(0)
	ds_write_b16_d16_hi v56, v92 offset:4352
	ds_write_b16 v56, v92 offset:22784
	ds_write_b16_d16_hi v56, v93 offset:4624
	ds_write_b16 v56, v93 offset:23056
	ds_write_b16_d16_hi v56, v94 offset:4896
	ds_write_b16 v56, v94 offset:23328
	ds_write_b16_d16_hi v56, v95 offset:5168
	ds_write_b16 v56, v95 offset:23600
	ds_write_b16_d16_hi v56, v96 offset:5440
	ds_write_b16 v56, v96 offset:23872
	ds_write_b16_d16_hi v56, v97 offset:5712
	ds_write_b16 v56, v97 offset:24144
	ds_write_b16_d16_hi v56, v98 offset:5984
	ds_write_b16 v56, v98 offset:24416
	ds_write_b16_d16_hi v56, v99 offset:6256
	ds_write_b16 v56, v99 offset:24688
	v_lshlrev_b32_e32 v84, 16, v116
	v_lshlrev_b32_e32 v85, 16, v117
	v_lshlrev_b32_e32 v86, 16, v118
	v_lshlrev_b32_e32 v87, 16, v119
	v_lshlrev_b32_e32 v88, 16, v120
	v_lshlrev_b32_e32 v89, 16, v121
	v_lshlrev_b32_e32 v90, 16, v122
	v_lshlrev_b32_e32 v91, 16, v123
	v_lshlrev_b32_e32 v100, 16, v124
	v_lshlrev_b32_e32 v101, 16, v125
	v_lshlrev_b32_e32 v102, 16, v126
	v_lshlrev_b32_e32 v103, 16, v127
	v_lshlrev_b32_e32 v104, 16, v128
	v_lshlrev_b32_e32 v105, 16, v129
	v_lshlrev_b32_e32 v106, 16, v130
	v_lshlrev_b32_e32 v107, 16, v131
	ds_read_u16 v68, v56 offset:27136
	ds_read_u16 v76, v56 offset:8704
	ds_read_u16 v69, v56 offset:27408
	ds_read_u16 v77, v56 offset:8976
	ds_read_u16 v70, v56 offset:27680
	ds_read_u16 v78, v56 offset:9248
	ds_read_u16 v71, v56 offset:27952
	ds_read_u16 v79, v56 offset:9520
	ds_read_u16 v72, v56 offset:28224
	ds_read_u16 v80, v56 offset:9792
	ds_read_u16 v73, v56 offset:28496
	ds_read_u16 v81, v56 offset:10064
	ds_read_u16 v74, v56 offset:28768
	ds_read_u16 v82, v56 offset:10336
	ds_read_u16 v75, v56 offset:29040
	ds_read_u16 v83, v56 offset:10608
	v_mul_f32_e32 v84, 0xbfb8aa3b, v84
	v_mul_f32_e32 v85, 0xbfb8aa3b, v85
	v_mul_f32_e32 v86, 0xbfb8aa3b, v86
	v_mul_f32_e32 v87, 0xbfb8aa3b, v87
	v_mul_f32_e32 v88, 0xbfb8aa3b, v88
	v_mul_f32_e32 v89, 0xbfb8aa3b, v89
	v_mul_f32_e32 v90, 0xbfb8aa3b, v90
	v_mul_f32_e32 v91, 0xbfb8aa3b, v91
	v_mul_f32_e32 v108, 0xbfb8aa3b, v100
	v_mul_f32_e32 v109, 0xbfb8aa3b, v101
	v_mul_f32_e32 v110, 0xbfb8aa3b, v102
	v_mul_f32_e32 v111, 0xbfb8aa3b, v103
	v_mul_f32_e32 v112, 0xbfb8aa3b, v104
	v_mul_f32_e32 v113, 0xbfb8aa3b, v105
	v_mul_f32_e32 v114, 0xbfb8aa3b, v106
	v_mul_f32_e32 v115, 0xbfb8aa3b, v107
	v_exp_f32_e32 v84, v84
	v_exp_f32_e32 v85, v85
	v_exp_f32_e32 v86, v86
	v_exp_f32_e32 v87, v87
	v_exp_f32_e32 v88, v88
	v_exp_f32_e32 v89, v89
	v_exp_f32_e32 v90, v90
	v_exp_f32_e32 v91, v91
	v_exp_f32_e32 v108, v108
	v_exp_f32_e32 v109, v109
	v_exp_f32_e32 v110, v110
	v_exp_f32_e32 v111, v111
	v_exp_f32_e32 v112, v112
	v_exp_f32_e32 v113, v113
	v_exp_f32_e32 v114, v114
	v_exp_f32_e32 v115, v115
	v_add_f32_e32 v84, 1.0, v84
	v_add_f32_e32 v85, 1.0, v85
	v_add_f32_e32 v86, 1.0, v86
	v_add_f32_e32 v87, 1.0, v87
	v_add_f32_e32 v88, 1.0, v88
	v_add_f32_e32 v89, 1.0, v89
	v_add_f32_e32 v90, 1.0, v90
	v_add_f32_e32 v91, 1.0, v91
	v_add_f32_e32 v108, 1.0, v108
	v_add_f32_e32 v109, 1.0, v109
	v_add_f32_e32 v110, 1.0, v110
	v_add_f32_e32 v111, 1.0, v111
	v_add_f32_e32 v112, 1.0, v112
	v_add_f32_e32 v113, 1.0, v113
	v_add_f32_e32 v114, 1.0, v114
	v_add_f32_e32 v115, 1.0, v115
	v_rcp_f32_e32 v84, v84
	v_rcp_f32_e32 v85, v85
	v_rcp_f32_e32 v86, v86
	v_rcp_f32_e32 v87, v87
	v_rcp_f32_e32 v88, v88
	v_rcp_f32_e32 v89, v89
	v_rcp_f32_e32 v90, v90
	v_rcp_f32_e32 v91, v91
	v_rcp_f32_e32 v108, v108
	v_rcp_f32_e32 v109, v109
	v_rcp_f32_e32 v110, v110
	v_rcp_f32_e32 v111, v111
	v_rcp_f32_e32 v112, v112
	v_rcp_f32_e32 v113, v113
	v_rcp_f32_e32 v114, v114
	v_rcp_f32_e32 v115, v115
	v_sub_f32_e32 v92, 1.0, v84
	v_sub_f32_e32 v93, 1.0, v85
	v_sub_f32_e32 v94, 1.0, v86
	v_sub_f32_e32 v95, 1.0, v87
	v_sub_f32_e32 v96, 1.0, v88
	v_sub_f32_e32 v97, 1.0, v89
	v_sub_f32_e32 v98, 1.0, v90
	v_sub_f32_e32 v99, 1.0, v91
	v_fma_f32 v84, v26, v84, v53
	v_fma_f32 v85, v26, v85, v53
	v_fma_f32 v86, v26, v86, v53
	v_fma_f32 v87, v26, v87, v53
	v_fma_f32 v88, v26, v88, v53
	v_fma_f32 v89, v26, v89, v53
	v_fma_f32 v90, v26, v90, v53
	v_fma_f32 v91, v26, v91, v53
	v_mul_f32_e32 v92, v26, v92
	v_mul_f32_e32 v93, v26, v93
	v_mul_f32_e32 v94, v26, v94
	v_mul_f32_e32 v95, v26, v95
	v_mul_f32_e32 v96, v26, v96
	v_mul_f32_e32 v97, v26, v97
	v_mul_f32_e32 v98, v26, v98
	v_mul_f32_e32 v99, v26, v99
	v_mul_f32_e32 v108, v108, v100
	v_mul_f32_e32 v109, v109, v101
	v_mul_f32_e32 v110, v110, v102
	v_mul_f32_e32 v111, v111, v103
	v_mul_f32_e32 v112, v112, v104
	v_mul_f32_e32 v113, v113, v105
	v_mul_f32_e32 v114, v114, v106
	v_mul_f32_e32 v115, v115, v107
	v_mul_f32_e32 v84, v27, v84
	v_mul_f32_e32 v85, v84, v85
	v_mul_f32_e32 v86, v85, v86
	v_mul_f32_e32 v87, v86, v87
	v_mul_f32_e32 v88, v87, v88
	v_mul_f32_e32 v89, v88, v89
	v_mul_f32_e32 v90, v89, v90
	v_mul_f32_e32 v91, v90, v91
	v_mov_b32_e32 v27, v91
	v_rcp_f32_e32 v100, v84
	v_rcp_f32_e32 v101, v85
	v_rcp_f32_e32 v102, v86
	v_rcp_f32_e32 v103, v87
	v_rcp_f32_e32 v104, v88
	v_rcp_f32_e32 v105, v89
	v_rcp_f32_e32 v106, v90
	v_rcp_f32_e32 v107, v91
	v_mul_f32_e32 v108, v84, v108
	v_mul_f32_e32 v109, v85, v109
	v_mul_f32_e32 v110, v86, v110
	v_mul_f32_e32 v111, v87, v111
	v_mul_f32_e32 v112, v88, v112
	v_mul_f32_e32 v113, v89, v113
	v_mul_f32_e32 v114, v90, v114
	v_mul_f32_e32 v115, v91, v115
	v_mul_f32_e32 v92, v92, v100
	v_mul_f32_e32 v93, v93, v101
	v_mul_f32_e32 v94, v94, v102
	v_mul_f32_e32 v95, v95, v103
	v_mul_f32_e32 v96, v96, v104
	v_mul_f32_e32 v97, v97, v105
	v_mul_f32_e32 v98, v98, v106
	v_mul_f32_e32 v99, v99, v107
	v_cvt_pk_bf16_f32 v92, v92, v108
	v_cvt_pk_bf16_f32 v93, v93, v109
	v_cvt_pk_bf16_f32 v94, v94, v110
	v_cvt_pk_bf16_f32 v95, v95, v111
	v_cvt_pk_bf16_f32 v96, v96, v112
	v_cvt_pk_bf16_f32 v97, v97, v113
	v_cvt_pk_bf16_f32 v98, v98, v114
	v_cvt_pk_bf16_f32 v99, v99, v115
	s_waitcnt lgkmcnt(0)
	ds_write_b16_d16_hi v56, v92 offset:6528
	ds_write_b16 v56, v92 offset:24960
	ds_write_b16_d16_hi v56, v93 offset:6800
	ds_write_b16 v56, v93 offset:25232
	ds_write_b16_d16_hi v56, v94 offset:7072
	ds_write_b16 v56, v94 offset:25504
	ds_write_b16_d16_hi v56, v95 offset:7344
	ds_write_b16 v56, v95 offset:25776
	ds_write_b16_d16_hi v56, v96 offset:7616
	ds_write_b16 v56, v96 offset:26048
	ds_write_b16_d16_hi v56, v97 offset:7888
	ds_write_b16 v56, v97 offset:26320
	ds_write_b16_d16_hi v56, v98 offset:8160
	ds_write_b16 v56, v98 offset:26592
	ds_write_b16_d16_hi v56, v99 offset:8432
	ds_write_b16 v56, v99 offset:26864
	v_lshlrev_b32_e32 v84, 16, v68
	v_lshlrev_b32_e32 v85, 16, v69
	v_lshlrev_b32_e32 v86, 16, v70
	v_lshlrev_b32_e32 v87, 16, v71
	v_lshlrev_b32_e32 v88, 16, v72
	v_lshlrev_b32_e32 v89, 16, v73
	v_lshlrev_b32_e32 v90, 16, v74
	v_lshlrev_b32_e32 v91, 16, v75
	v_lshlrev_b32_e32 v100, 16, v76
	v_lshlrev_b32_e32 v101, 16, v77
	v_lshlrev_b32_e32 v102, 16, v78
	v_lshlrev_b32_e32 v103, 16, v79
	v_lshlrev_b32_e32 v104, 16, v80
	v_lshlrev_b32_e32 v105, 16, v81
	v_lshlrev_b32_e32 v106, 16, v82
	v_lshlrev_b32_e32 v107, 16, v83
	ds_read_u16 v116, v56 offset:29312
	ds_read_u16 v124, v56 offset:10880
	ds_read_u16 v117, v56 offset:29584
	ds_read_u16 v125, v56 offset:11152
	ds_read_u16 v118, v56 offset:29856
	ds_read_u16 v126, v56 offset:11424
	ds_read_u16 v119, v56 offset:30128
	ds_read_u16 v127, v56 offset:11696
	ds_read_u16 v120, v56 offset:30400
	ds_read_u16 v128, v56 offset:11968
	ds_read_u16 v121, v56 offset:30672
	ds_read_u16 v129, v56 offset:12240
	ds_read_u16 v122, v56 offset:30944
	ds_read_u16 v130, v56 offset:12512
	ds_read_u16 v123, v56 offset:31216
	ds_read_u16 v131, v56 offset:12784
	v_mul_f32_e32 v84, 0xbfb8aa3b, v84
	v_mul_f32_e32 v85, 0xbfb8aa3b, v85
	v_mul_f32_e32 v86, 0xbfb8aa3b, v86
	v_mul_f32_e32 v87, 0xbfb8aa3b, v87
	v_mul_f32_e32 v88, 0xbfb8aa3b, v88
	v_mul_f32_e32 v89, 0xbfb8aa3b, v89
	v_mul_f32_e32 v90, 0xbfb8aa3b, v90
	v_mul_f32_e32 v91, 0xbfb8aa3b, v91
	v_mul_f32_e32 v108, 0xbfb8aa3b, v100
	v_mul_f32_e32 v109, 0xbfb8aa3b, v101
	v_mul_f32_e32 v110, 0xbfb8aa3b, v102
	v_mul_f32_e32 v111, 0xbfb8aa3b, v103
	v_mul_f32_e32 v112, 0xbfb8aa3b, v104
	v_mul_f32_e32 v113, 0xbfb8aa3b, v105
	v_mul_f32_e32 v114, 0xbfb8aa3b, v106
	v_mul_f32_e32 v115, 0xbfb8aa3b, v107
	v_exp_f32_e32 v84, v84
	v_exp_f32_e32 v85, v85
	v_exp_f32_e32 v86, v86
	v_exp_f32_e32 v87, v87
	v_exp_f32_e32 v88, v88
	v_exp_f32_e32 v89, v89
	v_exp_f32_e32 v90, v90
	v_exp_f32_e32 v91, v91
	v_exp_f32_e32 v108, v108
	v_exp_f32_e32 v109, v109
	v_exp_f32_e32 v110, v110
	v_exp_f32_e32 v111, v111
	v_exp_f32_e32 v112, v112
	v_exp_f32_e32 v113, v113
	v_exp_f32_e32 v114, v114
	v_exp_f32_e32 v115, v115
	v_add_f32_e32 v84, 1.0, v84
	v_add_f32_e32 v85, 1.0, v85
	v_add_f32_e32 v86, 1.0, v86
	v_add_f32_e32 v87, 1.0, v87
	v_add_f32_e32 v88, 1.0, v88
	v_add_f32_e32 v89, 1.0, v89
	v_add_f32_e32 v90, 1.0, v90
	v_add_f32_e32 v91, 1.0, v91
	v_add_f32_e32 v108, 1.0, v108
	v_add_f32_e32 v109, 1.0, v109
	v_add_f32_e32 v110, 1.0, v110
	v_add_f32_e32 v111, 1.0, v111
	v_add_f32_e32 v112, 1.0, v112
	v_add_f32_e32 v113, 1.0, v113
	v_add_f32_e32 v114, 1.0, v114
	v_add_f32_e32 v115, 1.0, v115
	v_rcp_f32_e32 v84, v84
	v_rcp_f32_e32 v85, v85
	v_rcp_f32_e32 v86, v86
	v_rcp_f32_e32 v87, v87
	v_rcp_f32_e32 v88, v88
	v_rcp_f32_e32 v89, v89
	v_rcp_f32_e32 v90, v90
	v_rcp_f32_e32 v91, v91
	v_rcp_f32_e32 v108, v108
	v_rcp_f32_e32 v109, v109
	v_rcp_f32_e32 v110, v110
	v_rcp_f32_e32 v111, v111
	v_rcp_f32_e32 v112, v112
	v_rcp_f32_e32 v113, v113
	v_rcp_f32_e32 v114, v114
	v_rcp_f32_e32 v115, v115
	v_sub_f32_e32 v92, 1.0, v84
	v_sub_f32_e32 v93, 1.0, v85
	v_sub_f32_e32 v94, 1.0, v86
	v_sub_f32_e32 v95, 1.0, v87
	v_sub_f32_e32 v96, 1.0, v88
	v_sub_f32_e32 v97, 1.0, v89
	v_sub_f32_e32 v98, 1.0, v90
	v_sub_f32_e32 v99, 1.0, v91
	v_fma_f32 v84, v26, v84, v53
	v_fma_f32 v85, v26, v85, v53
	v_fma_f32 v86, v26, v86, v53
	v_fma_f32 v87, v26, v87, v53
	v_fma_f32 v88, v26, v88, v53
	v_fma_f32 v89, v26, v89, v53
	v_fma_f32 v90, v26, v90, v53
	v_fma_f32 v91, v26, v91, v53
	v_mul_f32_e32 v92, v26, v92
	v_mul_f32_e32 v93, v26, v93
	v_mul_f32_e32 v94, v26, v94
	v_mul_f32_e32 v95, v26, v95
	v_mul_f32_e32 v96, v26, v96
	v_mul_f32_e32 v97, v26, v97
	v_mul_f32_e32 v98, v26, v98
	v_mul_f32_e32 v99, v26, v99
	v_mul_f32_e32 v108, v108, v100
	v_mul_f32_e32 v109, v109, v101
	v_mul_f32_e32 v110, v110, v102
	v_mul_f32_e32 v111, v111, v103
	v_mul_f32_e32 v112, v112, v104
	v_mul_f32_e32 v113, v113, v105
	v_mul_f32_e32 v114, v114, v106
	v_mul_f32_e32 v115, v115, v107
	v_mul_f32_e32 v84, v27, v84
	v_mul_f32_e32 v85, v84, v85
	v_mul_f32_e32 v86, v85, v86
	v_mul_f32_e32 v87, v86, v87
	v_mul_f32_e32 v88, v87, v88
	v_mul_f32_e32 v89, v88, v89
	v_mul_f32_e32 v90, v89, v90
	v_mul_f32_e32 v91, v90, v91
	v_mov_b32_e32 v27, v91
	v_rcp_f32_e32 v100, v84
	v_rcp_f32_e32 v101, v85
	v_rcp_f32_e32 v102, v86
	v_rcp_f32_e32 v103, v87
	v_rcp_f32_e32 v104, v88
	v_rcp_f32_e32 v105, v89
	v_rcp_f32_e32 v106, v90
	v_rcp_f32_e32 v107, v91
	v_mul_f32_e32 v108, v84, v108
	v_mul_f32_e32 v109, v85, v109
	v_mul_f32_e32 v110, v86, v110
	v_mul_f32_e32 v111, v87, v111
	v_mul_f32_e32 v112, v88, v112
	v_mul_f32_e32 v113, v89, v113
	v_mul_f32_e32 v114, v90, v114
	v_mul_f32_e32 v115, v91, v115
	v_mul_f32_e32 v92, v92, v100
	v_mul_f32_e32 v93, v93, v101
	v_mul_f32_e32 v94, v94, v102
	v_mul_f32_e32 v95, v95, v103
	v_mul_f32_e32 v96, v96, v104
	v_mul_f32_e32 v97, v97, v105
	v_mul_f32_e32 v98, v98, v106
	v_mul_f32_e32 v99, v99, v107
	v_cvt_pk_bf16_f32 v92, v92, v108
	v_cvt_pk_bf16_f32 v93, v93, v109
	v_cvt_pk_bf16_f32 v94, v94, v110
	v_cvt_pk_bf16_f32 v95, v95, v111
	v_cvt_pk_bf16_f32 v96, v96, v112
	v_cvt_pk_bf16_f32 v97, v97, v113
	v_cvt_pk_bf16_f32 v98, v98, v114
	v_cvt_pk_bf16_f32 v99, v99, v115
	s_waitcnt lgkmcnt(0)
	ds_write_b16_d16_hi v56, v92 offset:8704
	ds_write_b16 v56, v92 offset:27136
	ds_write_b16_d16_hi v56, v93 offset:8976
	ds_write_b16 v56, v93 offset:27408
	ds_write_b16_d16_hi v56, v94 offset:9248
	ds_write_b16 v56, v94 offset:27680
	ds_write_b16_d16_hi v56, v95 offset:9520
	ds_write_b16 v56, v95 offset:27952
	ds_write_b16_d16_hi v56, v96 offset:9792
	ds_write_b16 v56, v96 offset:28224
	ds_write_b16_d16_hi v56, v97 offset:10064
	ds_write_b16 v56, v97 offset:28496
	ds_write_b16_d16_hi v56, v98 offset:10336
	ds_write_b16 v56, v98 offset:28768
	ds_write_b16_d16_hi v56, v99 offset:10608
	ds_write_b16 v56, v99 offset:29040
	v_lshlrev_b32_e32 v84, 16, v116
	v_lshlrev_b32_e32 v85, 16, v117
	v_lshlrev_b32_e32 v86, 16, v118
	v_lshlrev_b32_e32 v87, 16, v119
	v_lshlrev_b32_e32 v88, 16, v120
	v_lshlrev_b32_e32 v89, 16, v121
	v_lshlrev_b32_e32 v90, 16, v122
	v_lshlrev_b32_e32 v91, 16, v123
	v_lshlrev_b32_e32 v100, 16, v124
	v_lshlrev_b32_e32 v101, 16, v125
	v_lshlrev_b32_e32 v102, 16, v126
	v_lshlrev_b32_e32 v103, 16, v127
	v_lshlrev_b32_e32 v104, 16, v128
	v_lshlrev_b32_e32 v105, 16, v129
	v_lshlrev_b32_e32 v106, 16, v130
	v_lshlrev_b32_e32 v107, 16, v131
	ds_read_u16 v68, v56 offset:31488
	ds_read_u16 v76, v56 offset:13056
	ds_read_u16 v69, v56 offset:31760
	ds_read_u16 v77, v56 offset:13328
	ds_read_u16 v70, v56 offset:32032
	ds_read_u16 v78, v56 offset:13600
	ds_read_u16 v71, v56 offset:32304
	ds_read_u16 v79, v56 offset:13872
	ds_read_u16 v72, v56 offset:32576
	ds_read_u16 v80, v56 offset:14144
	ds_read_u16 v73, v56 offset:32848
	ds_read_u16 v81, v56 offset:14416
	ds_read_u16 v74, v56 offset:33120
	ds_read_u16 v82, v56 offset:14688
	ds_read_u16 v75, v56 offset:33392
	ds_read_u16 v83, v56 offset:14960
	v_mul_f32_e32 v84, 0xbfb8aa3b, v84
	v_mul_f32_e32 v85, 0xbfb8aa3b, v85
	v_mul_f32_e32 v86, 0xbfb8aa3b, v86
	v_mul_f32_e32 v87, 0xbfb8aa3b, v87
	v_mul_f32_e32 v88, 0xbfb8aa3b, v88
	v_mul_f32_e32 v89, 0xbfb8aa3b, v89
	v_mul_f32_e32 v90, 0xbfb8aa3b, v90
	v_mul_f32_e32 v91, 0xbfb8aa3b, v91
	v_mul_f32_e32 v108, 0xbfb8aa3b, v100
	v_mul_f32_e32 v109, 0xbfb8aa3b, v101
	v_mul_f32_e32 v110, 0xbfb8aa3b, v102
	v_mul_f32_e32 v111, 0xbfb8aa3b, v103
	v_mul_f32_e32 v112, 0xbfb8aa3b, v104
	v_mul_f32_e32 v113, 0xbfb8aa3b, v105
	v_mul_f32_e32 v114, 0xbfb8aa3b, v106
	v_mul_f32_e32 v115, 0xbfb8aa3b, v107
	v_exp_f32_e32 v84, v84
	v_exp_f32_e32 v85, v85
	v_exp_f32_e32 v86, v86
	v_exp_f32_e32 v87, v87
	v_exp_f32_e32 v88, v88
	v_exp_f32_e32 v89, v89
	v_exp_f32_e32 v90, v90
	v_exp_f32_e32 v91, v91
	v_exp_f32_e32 v108, v108
	v_exp_f32_e32 v109, v109
	v_exp_f32_e32 v110, v110
	v_exp_f32_e32 v111, v111
	v_exp_f32_e32 v112, v112
	v_exp_f32_e32 v113, v113
	v_exp_f32_e32 v114, v114
	v_exp_f32_e32 v115, v115
	v_add_f32_e32 v84, 1.0, v84
	v_add_f32_e32 v85, 1.0, v85
	v_add_f32_e32 v86, 1.0, v86
	v_add_f32_e32 v87, 1.0, v87
	v_add_f32_e32 v88, 1.0, v88
	v_add_f32_e32 v89, 1.0, v89
	v_add_f32_e32 v90, 1.0, v90
	v_add_f32_e32 v91, 1.0, v91
	v_add_f32_e32 v108, 1.0, v108
	v_add_f32_e32 v109, 1.0, v109
	v_add_f32_e32 v110, 1.0, v110
	v_add_f32_e32 v111, 1.0, v111
	v_add_f32_e32 v112, 1.0, v112
	v_add_f32_e32 v113, 1.0, v113
	v_add_f32_e32 v114, 1.0, v114
	v_add_f32_e32 v115, 1.0, v115
	v_rcp_f32_e32 v84, v84
	v_rcp_f32_e32 v85, v85
	v_rcp_f32_e32 v86, v86
	v_rcp_f32_e32 v87, v87
	v_rcp_f32_e32 v88, v88
	v_rcp_f32_e32 v89, v89
	v_rcp_f32_e32 v90, v90
	v_rcp_f32_e32 v91, v91
	v_rcp_f32_e32 v108, v108
	v_rcp_f32_e32 v109, v109
	v_rcp_f32_e32 v110, v110
	v_rcp_f32_e32 v111, v111
	v_rcp_f32_e32 v112, v112
	v_rcp_f32_e32 v113, v113
	v_rcp_f32_e32 v114, v114
	v_rcp_f32_e32 v115, v115
	v_sub_f32_e32 v92, 1.0, v84
	v_sub_f32_e32 v93, 1.0, v85
	v_sub_f32_e32 v94, 1.0, v86
	v_sub_f32_e32 v95, 1.0, v87
	v_sub_f32_e32 v96, 1.0, v88
	v_sub_f32_e32 v97, 1.0, v89
	v_sub_f32_e32 v98, 1.0, v90
	v_sub_f32_e32 v99, 1.0, v91
	v_fma_f32 v84, v26, v84, v53
	v_fma_f32 v85, v26, v85, v53
	v_fma_f32 v86, v26, v86, v53
	v_fma_f32 v87, v26, v87, v53
	v_fma_f32 v88, v26, v88, v53
	v_fma_f32 v89, v26, v89, v53
	v_fma_f32 v90, v26, v90, v53
	v_fma_f32 v91, v26, v91, v53
	v_mul_f32_e32 v92, v26, v92
	v_mul_f32_e32 v93, v26, v93
	v_mul_f32_e32 v94, v26, v94
	v_mul_f32_e32 v95, v26, v95
	v_mul_f32_e32 v96, v26, v96
	v_mul_f32_e32 v97, v26, v97
	v_mul_f32_e32 v98, v26, v98
	v_mul_f32_e32 v99, v26, v99
	v_mul_f32_e32 v108, v108, v100
	v_mul_f32_e32 v109, v109, v101
	v_mul_f32_e32 v110, v110, v102
	v_mul_f32_e32 v111, v111, v103
	v_mul_f32_e32 v112, v112, v104
	v_mul_f32_e32 v113, v113, v105
	v_mul_f32_e32 v114, v114, v106
	v_mul_f32_e32 v115, v115, v107
	v_mul_f32_e32 v84, v27, v84
	v_mul_f32_e32 v85, v84, v85
	v_mul_f32_e32 v86, v85, v86
	v_mul_f32_e32 v87, v86, v87
	v_mul_f32_e32 v88, v87, v88
	v_mul_f32_e32 v89, v88, v89
	v_mul_f32_e32 v90, v89, v90
	v_mul_f32_e32 v91, v90, v91
	v_mov_b32_e32 v27, v91
	v_rcp_f32_e32 v100, v84
	v_rcp_f32_e32 v101, v85
	v_rcp_f32_e32 v102, v86
	v_rcp_f32_e32 v103, v87
	v_rcp_f32_e32 v104, v88
	v_rcp_f32_e32 v105, v89
	v_rcp_f32_e32 v106, v90
	v_rcp_f32_e32 v107, v91
	v_mul_f32_e32 v108, v84, v108
	v_mul_f32_e32 v109, v85, v109
	v_mul_f32_e32 v110, v86, v110
	v_mul_f32_e32 v111, v87, v111
	v_mul_f32_e32 v112, v88, v112
	v_mul_f32_e32 v113, v89, v113
	v_mul_f32_e32 v114, v90, v114
	v_mul_f32_e32 v115, v91, v115
	v_mul_f32_e32 v92, v92, v100
	v_mul_f32_e32 v93, v93, v101
	v_mul_f32_e32 v94, v94, v102
	v_mul_f32_e32 v95, v95, v103
	v_mul_f32_e32 v96, v96, v104
	v_mul_f32_e32 v97, v97, v105
	v_mul_f32_e32 v98, v98, v106
	v_mul_f32_e32 v99, v99, v107
	v_cvt_pk_bf16_f32 v92, v92, v108
	v_cvt_pk_bf16_f32 v93, v93, v109
	v_cvt_pk_bf16_f32 v94, v94, v110
	v_cvt_pk_bf16_f32 v95, v95, v111
	v_cvt_pk_bf16_f32 v96, v96, v112
	v_cvt_pk_bf16_f32 v97, v97, v113
	v_cvt_pk_bf16_f32 v98, v98, v114
	v_cvt_pk_bf16_f32 v99, v99, v115
	s_waitcnt lgkmcnt(0)
	ds_write_b16_d16_hi v56, v92 offset:10880
	ds_write_b16 v56, v92 offset:29312
	ds_write_b16_d16_hi v56, v93 offset:11152
	ds_write_b16 v56, v93 offset:29584
	ds_write_b16_d16_hi v56, v94 offset:11424
	ds_write_b16 v56, v94 offset:29856
	ds_write_b16_d16_hi v56, v95 offset:11696
	ds_write_b16 v56, v95 offset:30128
	ds_write_b16_d16_hi v56, v96 offset:11968
	ds_write_b16 v56, v96 offset:30400
	ds_write_b16_d16_hi v56, v97 offset:12240
	ds_write_b16 v56, v97 offset:30672
	ds_write_b16_d16_hi v56, v98 offset:12512
	ds_write_b16 v56, v98 offset:30944
	ds_write_b16_d16_hi v56, v99 offset:12784
	ds_write_b16 v56, v99 offset:31216
	v_lshlrev_b32_e32 v84, 16, v68
	v_lshlrev_b32_e32 v85, 16, v69
	v_lshlrev_b32_e32 v86, 16, v70
	v_lshlrev_b32_e32 v87, 16, v71
	v_lshlrev_b32_e32 v88, 16, v72
	v_lshlrev_b32_e32 v89, 16, v73
	v_lshlrev_b32_e32 v90, 16, v74
	v_lshlrev_b32_e32 v91, 16, v75
	v_lshlrev_b32_e32 v100, 16, v76
	v_lshlrev_b32_e32 v101, 16, v77
	v_lshlrev_b32_e32 v102, 16, v78
	v_lshlrev_b32_e32 v103, 16, v79
	v_lshlrev_b32_e32 v104, 16, v80
	v_lshlrev_b32_e32 v105, 16, v81
	v_lshlrev_b32_e32 v106, 16, v82
	v_lshlrev_b32_e32 v107, 16, v83
	ds_read_u16 v116, v56 offset:33664
	ds_read_u16 v124, v56 offset:15232
	ds_read_u16 v117, v56 offset:33936
	ds_read_u16 v125, v56 offset:15504
	ds_read_u16 v118, v56 offset:34208
	ds_read_u16 v126, v56 offset:15776
	ds_read_u16 v119, v56 offset:34480
	ds_read_u16 v127, v56 offset:16048
	ds_read_u16 v120, v56 offset:34752
	ds_read_u16 v128, v56 offset:16320
	ds_read_u16 v121, v56 offset:35024
	ds_read_u16 v129, v56 offset:16592
	ds_read_u16 v122, v56 offset:35296
	ds_read_u16 v130, v56 offset:16864
	ds_read_u16 v123, v56 offset:35568
	ds_read_u16 v131, v56 offset:17136
	v_mul_f32_e32 v84, 0xbfb8aa3b, v84
	v_mul_f32_e32 v85, 0xbfb8aa3b, v85
	v_mul_f32_e32 v86, 0xbfb8aa3b, v86
	v_mul_f32_e32 v87, 0xbfb8aa3b, v87
	v_mul_f32_e32 v88, 0xbfb8aa3b, v88
	v_mul_f32_e32 v89, 0xbfb8aa3b, v89
	v_mul_f32_e32 v90, 0xbfb8aa3b, v90
	v_mul_f32_e32 v91, 0xbfb8aa3b, v91
	v_mul_f32_e32 v108, 0xbfb8aa3b, v100
	v_mul_f32_e32 v109, 0xbfb8aa3b, v101
	v_mul_f32_e32 v110, 0xbfb8aa3b, v102
	v_mul_f32_e32 v111, 0xbfb8aa3b, v103
	v_mul_f32_e32 v112, 0xbfb8aa3b, v104
	v_mul_f32_e32 v113, 0xbfb8aa3b, v105
	v_mul_f32_e32 v114, 0xbfb8aa3b, v106
	v_mul_f32_e32 v115, 0xbfb8aa3b, v107
	v_exp_f32_e32 v84, v84
	v_exp_f32_e32 v85, v85
	v_exp_f32_e32 v86, v86
	v_exp_f32_e32 v87, v87
	v_exp_f32_e32 v88, v88
	v_exp_f32_e32 v89, v89
	v_exp_f32_e32 v90, v90
	v_exp_f32_e32 v91, v91
	v_exp_f32_e32 v108, v108
	v_exp_f32_e32 v109, v109
	v_exp_f32_e32 v110, v110
	v_exp_f32_e32 v111, v111
	v_exp_f32_e32 v112, v112
	v_exp_f32_e32 v113, v113
	v_exp_f32_e32 v114, v114
	v_exp_f32_e32 v115, v115
	v_add_f32_e32 v84, 1.0, v84
	v_add_f32_e32 v85, 1.0, v85
	v_add_f32_e32 v86, 1.0, v86
	v_add_f32_e32 v87, 1.0, v87
	v_add_f32_e32 v88, 1.0, v88
	v_add_f32_e32 v89, 1.0, v89
	v_add_f32_e32 v90, 1.0, v90
	v_add_f32_e32 v91, 1.0, v91
	v_add_f32_e32 v108, 1.0, v108
	v_add_f32_e32 v109, 1.0, v109
	v_add_f32_e32 v110, 1.0, v110
	v_add_f32_e32 v111, 1.0, v111
	v_add_f32_e32 v112, 1.0, v112
	v_add_f32_e32 v113, 1.0, v113
	v_add_f32_e32 v114, 1.0, v114
	v_add_f32_e32 v115, 1.0, v115
	v_rcp_f32_e32 v84, v84
	v_rcp_f32_e32 v85, v85
	v_rcp_f32_e32 v86, v86
	v_rcp_f32_e32 v87, v87
	v_rcp_f32_e32 v88, v88
	v_rcp_f32_e32 v89, v89
	v_rcp_f32_e32 v90, v90
	v_rcp_f32_e32 v91, v91
	v_rcp_f32_e32 v108, v108
	v_rcp_f32_e32 v109, v109
	v_rcp_f32_e32 v110, v110
	v_rcp_f32_e32 v111, v111
	v_rcp_f32_e32 v112, v112
	v_rcp_f32_e32 v113, v113
	v_rcp_f32_e32 v114, v114
	v_rcp_f32_e32 v115, v115
	v_sub_f32_e32 v92, 1.0, v84
	v_sub_f32_e32 v93, 1.0, v85
	v_sub_f32_e32 v94, 1.0, v86
	v_sub_f32_e32 v95, 1.0, v87
	v_sub_f32_e32 v96, 1.0, v88
	v_sub_f32_e32 v97, 1.0, v89
	v_sub_f32_e32 v98, 1.0, v90
	v_sub_f32_e32 v99, 1.0, v91
	v_fma_f32 v84, v26, v84, v53
	v_fma_f32 v85, v26, v85, v53
	v_fma_f32 v86, v26, v86, v53
	v_fma_f32 v87, v26, v87, v53
	v_fma_f32 v88, v26, v88, v53
	v_fma_f32 v89, v26, v89, v53
	v_fma_f32 v90, v26, v90, v53
	v_fma_f32 v91, v26, v91, v53
	v_mul_f32_e32 v92, v26, v92
	v_mul_f32_e32 v93, v26, v93
	v_mul_f32_e32 v94, v26, v94
	v_mul_f32_e32 v95, v26, v95
	v_mul_f32_e32 v96, v26, v96
	v_mul_f32_e32 v97, v26, v97
	v_mul_f32_e32 v98, v26, v98
	v_mul_f32_e32 v99, v26, v99
	v_mul_f32_e32 v108, v108, v100
	v_mul_f32_e32 v109, v109, v101
	v_mul_f32_e32 v110, v110, v102
	v_mul_f32_e32 v111, v111, v103
	v_mul_f32_e32 v112, v112, v104
	v_mul_f32_e32 v113, v113, v105
	v_mul_f32_e32 v114, v114, v106
	v_mul_f32_e32 v115, v115, v107
	v_mul_f32_e32 v84, v27, v84
	v_mul_f32_e32 v85, v84, v85
	v_mul_f32_e32 v86, v85, v86
	v_mul_f32_e32 v87, v86, v87
	v_mul_f32_e32 v88, v87, v88
	v_mul_f32_e32 v89, v88, v89
	v_mul_f32_e32 v90, v89, v90
	v_mul_f32_e32 v91, v90, v91
	v_mov_b32_e32 v27, v91
	v_rcp_f32_e32 v100, v84
	v_rcp_f32_e32 v101, v85
	v_rcp_f32_e32 v102, v86
	v_rcp_f32_e32 v103, v87
	v_rcp_f32_e32 v104, v88
	v_rcp_f32_e32 v105, v89
	v_rcp_f32_e32 v106, v90
	v_rcp_f32_e32 v107, v91
	v_mul_f32_e32 v108, v84, v108
	v_mul_f32_e32 v109, v85, v109
	v_mul_f32_e32 v110, v86, v110
	v_mul_f32_e32 v111, v87, v111
	v_mul_f32_e32 v112, v88, v112
	v_mul_f32_e32 v113, v89, v113
	v_mul_f32_e32 v114, v90, v114
	v_mul_f32_e32 v115, v91, v115
	v_mul_f32_e32 v92, v92, v100
	v_mul_f32_e32 v93, v93, v101
	v_mul_f32_e32 v94, v94, v102
	v_mul_f32_e32 v95, v95, v103
	v_mul_f32_e32 v96, v96, v104
	v_mul_f32_e32 v97, v97, v105
	v_mul_f32_e32 v98, v98, v106
	v_mul_f32_e32 v99, v99, v107
	v_cvt_pk_bf16_f32 v92, v92, v108
	v_cvt_pk_bf16_f32 v93, v93, v109
	v_cvt_pk_bf16_f32 v94, v94, v110
	v_cvt_pk_bf16_f32 v95, v95, v111
	v_cvt_pk_bf16_f32 v96, v96, v112
	v_cvt_pk_bf16_f32 v97, v97, v113
	v_cvt_pk_bf16_f32 v98, v98, v114
	v_cvt_pk_bf16_f32 v99, v99, v115
	s_waitcnt lgkmcnt(0)
	ds_write_b16_d16_hi v56, v92 offset:13056
	ds_write_b16 v56, v92 offset:31488
	ds_write_b16_d16_hi v56, v93 offset:13328
	ds_write_b16 v56, v93 offset:31760
	ds_write_b16_d16_hi v56, v94 offset:13600
	ds_write_b16 v56, v94 offset:32032
	ds_write_b16_d16_hi v56, v95 offset:13872
	ds_write_b16 v56, v95 offset:32304
	ds_write_b16_d16_hi v56, v96 offset:14144
	ds_write_b16 v56, v96 offset:32576
	ds_write_b16_d16_hi v56, v97 offset:14416
	ds_write_b16 v56, v97 offset:32848
	ds_write_b16_d16_hi v56, v98 offset:14688
	ds_write_b16 v56, v98 offset:33120
	ds_write_b16_d16_hi v56, v99 offset:14960
	ds_write_b16 v56, v99 offset:33392
	v_lshlrev_b32_e32 v84, 16, v116
	v_lshlrev_b32_e32 v85, 16, v117
	v_lshlrev_b32_e32 v86, 16, v118
	v_lshlrev_b32_e32 v87, 16, v119
	v_lshlrev_b32_e32 v88, 16, v120
	v_lshlrev_b32_e32 v89, 16, v121
	v_lshlrev_b32_e32 v90, 16, v122
	v_lshlrev_b32_e32 v91, 16, v123
	v_lshlrev_b32_e32 v100, 16, v124
	v_lshlrev_b32_e32 v101, 16, v125
	v_lshlrev_b32_e32 v102, 16, v126
	v_lshlrev_b32_e32 v103, 16, v127
	v_lshlrev_b32_e32 v104, 16, v128
	v_lshlrev_b32_e32 v105, 16, v129
	v_lshlrev_b32_e32 v106, 16, v130
	v_lshlrev_b32_e32 v107, 16, v131
	v_mul_f32_e32 v84, 0xbfb8aa3b, v84
	v_mul_f32_e32 v85, 0xbfb8aa3b, v85
	v_mul_f32_e32 v86, 0xbfb8aa3b, v86
	v_mul_f32_e32 v87, 0xbfb8aa3b, v87
	v_mul_f32_e32 v88, 0xbfb8aa3b, v88
	v_mul_f32_e32 v89, 0xbfb8aa3b, v89
	v_mul_f32_e32 v90, 0xbfb8aa3b, v90
	v_mul_f32_e32 v91, 0xbfb8aa3b, v91
	v_mul_f32_e32 v108, 0xbfb8aa3b, v100
	v_mul_f32_e32 v109, 0xbfb8aa3b, v101
	v_mul_f32_e32 v110, 0xbfb8aa3b, v102
	v_mul_f32_e32 v111, 0xbfb8aa3b, v103
	v_mul_f32_e32 v112, 0xbfb8aa3b, v104
	v_mul_f32_e32 v113, 0xbfb8aa3b, v105
	v_mul_f32_e32 v114, 0xbfb8aa3b, v106
	v_mul_f32_e32 v115, 0xbfb8aa3b, v107
	v_exp_f32_e32 v84, v84
	v_exp_f32_e32 v85, v85
	v_exp_f32_e32 v86, v86
	v_exp_f32_e32 v87, v87
	v_exp_f32_e32 v88, v88
	v_exp_f32_e32 v89, v89
	v_exp_f32_e32 v90, v90
	v_exp_f32_e32 v91, v91
	v_exp_f32_e32 v108, v108
	v_exp_f32_e32 v109, v109
	v_exp_f32_e32 v110, v110
	v_exp_f32_e32 v111, v111
	v_exp_f32_e32 v112, v112
	v_exp_f32_e32 v113, v113
	v_exp_f32_e32 v114, v114
	v_exp_f32_e32 v115, v115
	v_add_f32_e32 v84, 1.0, v84
	v_add_f32_e32 v85, 1.0, v85
	v_add_f32_e32 v86, 1.0, v86
	v_add_f32_e32 v87, 1.0, v87
	v_add_f32_e32 v88, 1.0, v88
	v_add_f32_e32 v89, 1.0, v89
	v_add_f32_e32 v90, 1.0, v90
	v_add_f32_e32 v91, 1.0, v91
	v_add_f32_e32 v108, 1.0, v108
	v_add_f32_e32 v109, 1.0, v109
	v_add_f32_e32 v110, 1.0, v110
	v_add_f32_e32 v111, 1.0, v111
	v_add_f32_e32 v112, 1.0, v112
	v_add_f32_e32 v113, 1.0, v113
	v_add_f32_e32 v114, 1.0, v114
	v_add_f32_e32 v115, 1.0, v115
	v_rcp_f32_e32 v84, v84
	v_rcp_f32_e32 v85, v85
	v_rcp_f32_e32 v86, v86
	v_rcp_f32_e32 v87, v87
	v_rcp_f32_e32 v88, v88
	v_rcp_f32_e32 v89, v89
	v_rcp_f32_e32 v90, v90
	v_rcp_f32_e32 v91, v91
	v_rcp_f32_e32 v108, v108
	v_rcp_f32_e32 v109, v109
	v_rcp_f32_e32 v110, v110
	v_rcp_f32_e32 v111, v111
	v_rcp_f32_e32 v112, v112
	v_rcp_f32_e32 v113, v113
	v_rcp_f32_e32 v114, v114
	v_rcp_f32_e32 v115, v115
	v_sub_f32_e32 v92, 1.0, v84
	v_sub_f32_e32 v93, 1.0, v85
	v_sub_f32_e32 v94, 1.0, v86
	v_sub_f32_e32 v95, 1.0, v87
	v_sub_f32_e32 v96, 1.0, v88
	v_sub_f32_e32 v97, 1.0, v89
	v_sub_f32_e32 v98, 1.0, v90
	v_sub_f32_e32 v99, 1.0, v91
	v_fma_f32 v84, v26, v84, v53
	v_fma_f32 v85, v26, v85, v53
	v_fma_f32 v86, v26, v86, v53
	v_fma_f32 v87, v26, v87, v53
	v_fma_f32 v88, v26, v88, v53
	v_fma_f32 v89, v26, v89, v53
	v_fma_f32 v90, v26, v90, v53
	v_fma_f32 v91, v26, v91, v53
	v_mul_f32_e32 v92, v26, v92
	v_mul_f32_e32 v93, v26, v93
	v_mul_f32_e32 v94, v26, v94
	v_mul_f32_e32 v95, v26, v95
	v_mul_f32_e32 v96, v26, v96
	v_mul_f32_e32 v97, v26, v97
	v_mul_f32_e32 v98, v26, v98
	v_mul_f32_e32 v99, v26, v99
	v_mul_f32_e32 v108, v108, v100
	v_mul_f32_e32 v109, v109, v101
	v_mul_f32_e32 v110, v110, v102
	v_mul_f32_e32 v111, v111, v103
	v_mul_f32_e32 v112, v112, v104
	v_mul_f32_e32 v113, v113, v105
	v_mul_f32_e32 v114, v114, v106
	v_mul_f32_e32 v115, v115, v107
	v_mul_f32_e32 v84, v27, v84
	v_mul_f32_e32 v85, v84, v85
	v_mul_f32_e32 v86, v85, v86
	v_mul_f32_e32 v87, v86, v87
	v_mul_f32_e32 v88, v87, v88
	v_mul_f32_e32 v89, v88, v89
	v_mul_f32_e32 v90, v89, v90
	v_mul_f32_e32 v91, v90, v91
	v_mov_b32_e32 v27, v91
	v_rcp_f32_e32 v100, v84
	v_rcp_f32_e32 v101, v85
	v_rcp_f32_e32 v102, v86
	v_rcp_f32_e32 v103, v87
	v_rcp_f32_e32 v104, v88
	v_rcp_f32_e32 v105, v89
	v_rcp_f32_e32 v106, v90
	v_rcp_f32_e32 v107, v91
	v_mul_f32_e32 v108, v84, v108
	v_mul_f32_e32 v109, v85, v109
	v_mul_f32_e32 v110, v86, v110
	v_mul_f32_e32 v111, v87, v111
	v_mul_f32_e32 v112, v88, v112
	v_mul_f32_e32 v113, v89, v113
	v_mul_f32_e32 v114, v90, v114
	v_mul_f32_e32 v115, v91, v115
	v_mul_f32_e32 v92, v92, v100
	v_mul_f32_e32 v93, v93, v101
	v_mul_f32_e32 v94, v94, v102
	v_mul_f32_e32 v95, v95, v103
	v_mul_f32_e32 v96, v96, v104
	v_mul_f32_e32 v97, v97, v105
	v_mul_f32_e32 v98, v98, v106
	v_mul_f32_e32 v99, v99, v107
	v_cvt_pk_bf16_f32 v92, v92, v108
	v_cvt_pk_bf16_f32 v93, v93, v109
	v_cvt_pk_bf16_f32 v94, v94, v110
	v_cvt_pk_bf16_f32 v95, v95, v111
	v_cvt_pk_bf16_f32 v96, v96, v112
	v_cvt_pk_bf16_f32 v97, v97, v113
	v_cvt_pk_bf16_f32 v98, v98, v114
	v_cvt_pk_bf16_f32 v99, v99, v115
	s_waitcnt lgkmcnt(0)
	ds_write_b16_d16_hi v56, v92 offset:15232
	ds_write_b16 v56, v92 offset:33664
	ds_write_b16_d16_hi v56, v93 offset:15504
	ds_write_b16 v56, v93 offset:33936
	ds_write_b16_d16_hi v56, v94 offset:15776
	ds_write_b16 v56, v94 offset:34208
	ds_write_b16_d16_hi v56, v95 offset:16048
	ds_write_b16 v56, v95 offset:34480
	ds_write_b16_d16_hi v56, v96 offset:16320
	ds_write_b16 v56, v96 offset:34752
	ds_write_b16_d16_hi v56, v97 offset:16592
	ds_write_b16 v56, v97 offset:35024
	ds_write_b16_d16_hi v56, v98 offset:16864
	ds_write_b16 v56, v98 offset:35296
	ds_write_b16_d16_hi v56, v99 offset:17136
	ds_write_b16 v56, v99 offset:35568
	s_branch .LBB0_900
